# speedup vs baseline: 1.0684x; 1.0047x over previous
; template <bool SHIFT>
; __device__ __forceinline__ void gemm_issue(const ushort_t* __restrict__ P, int ldp, const ushort_t* __restrict__ Q, int ldq,
;                                            int k0, int grow0, const ushort_t* zrow, char* bufA, char* bufB) {
;   const int tid = opaque_tid();
;   const int sc = ((tid & 7) ^ ((tid >> 3) & 7)) * 8;
;   const unsigned voa = (unsigned)(((tid >> 3) * ldp + sc) * 2);
;   const unsigned vob = (unsigned)(((tid >> 3) * ldq + sc) * 2);
; #pragma unroll
;   for (int i = 0; i < 4; ++i) {
;     const char* src;
;     if (SHIFT && k0 >= 1024) {
;       src = (const char*)P + ((long)(i * 32 - 1) * ldp + (k0 - 1024)) * 2 + voa;
;       if (((grow0 + (tid >> 3) + i * 32) & 4095) == 0) src = (const char*)zrow + sc * 2;
;     } else {
;       src = (const char*)P + ((long)(i * 32) * ldp + k0) * 2 + voa;
;     }
;     __builtin_amdgcn_global_load_lds((const unsigned*)src, (unsigned*)(bufA + tid * 16 + i * 4096), 16, 0, 0);
;     const char* srb = (const char*)Q + ((long)(i * 32) * ldq + k0) * 2 + vob;
;     __builtin_amdgcn_global_load_lds((const unsigned*)srb, (unsigned*)(bufB + tid * 16 + i * 4096), 16, 0, 0);
;   }
; }
;   const int tid = opaque_tid(), lane = tid & 63, wave = tid >> 6, wp = wave >> 1, wq = wave & 1, lr = lane & 15, g = lane >> 4;
;   if (!ACCUM) {
; #pragma unroll
;     for (int i = 0; i < 4; ++i)
; #pragma unroll
;       for (int j = 0; j < 4; ++j) acc[i][j] = (f32x4){0.f, 0.f, 0.f, 0.f};
;   }
;   const int fbase = lr * 128 + ((g ^ (lr & 7)) << 4);
;   const int nk = K >> 6;
;   __syncthreads();
;   gemm_issue<SHIFT>(P, ldp, Q, ldq, 0, grow0, zrow, smem, smem + 16384);
; __device__ __forceinline__ void phase_ret_passC(const Params& p, char* smem) {
;     ...
;     store_tile(scr, 128, Cs, [&](float v, int n, int m) { return (n >= m) ? v * __builtin_amdgcn_exp2f((float)(n - m) * l2g) : 0.f; });
;     __threadfence();
;     __syncthreads();
;     const int c16 = tid & 15, rgrp = tid >> 4;
;     float ssp[8];
; #pragma unroll
;     for (int it = 0; it < 8; ++it) ssp[it] = 0.f;
; #pragma unroll 1
;     for (int eh = 0; eh < 2; ++eh) {
;       gemm_core<false, false>(QR + tok0 * 1024 + hh * 256, 1024, ST + ((long)((bh * 32 + c) * 256 + eh * 128)) * 256, 256, 256, smem, acc);
;       int nb = wp * 64 + g * 4 + 1;
;       asm volatile("" : "+v"(nb));
.LBB0_1689:
	s_or_b64 exec, exec, s[90:91]
	v_add_u32_e32 v17, v4, v21
	v_cvt_f32_i32_e32 v17, v17
	v_sub_u32_e32 v21, v4, v13
	v_cvt_f32_i32_e32 v21, v21
	v_sub_u32_e32 v20, v4, v12
	v_mul_f32_e32 v17, v109, v17
	v_exp_f32_e32 v17, v17
	v_cvt_f32_i32_e32 v20, v20
	v_sub_u32_e32 v23, v4, v9
	v_cvt_f32_i32_e32 v23, v23
	s_waitcnt lgkmcnt(2)
	v_mul_f32_e32 v24, v17, v16
	v_mul_f32_e32 v16, v109, v21
	v_sub_u32_e32 v17, v4, v10
	v_sub_u32_e32 v21, v4, v11
	v_cvt_f32_i32_e32 v17, v17
	v_cvt_f32_i32_e32 v22, v21
	v_mul_f32_e32 v20, v109, v20
	v_exp_f32_e32 v21, v16
	v_mul_f32_e32 v16, v109, v17
	v_mul_f32_e32 v17, v109, v22
	v_sub_u32_e32 v22, v4, v8
	v_exp_f32_e32 v20, v20
	v_cvt_f32_i32_e32 v22, v22
	v_exp_f32_e32 v16, v16
	v_exp_f32_e32 v17, v17
	v_mul_f32_e32 v23, v109, v23
	v_mul_f32_e32 v22, v109, v22
	v_cmp_gt_i32_e32 vcc, v4, v19
	s_waitcnt lgkmcnt(0)
	v_pk_mul_f32 v[20:21], v[20:21], v[0:1]
	v_exp_f32_e32 v22, v22
	v_exp_f32_e32 v23, v23
	v_cndmask_b32_e32 v19, 0, v24, vcc
	v_cvt_pk_bf16_f32 v1, v20, v21
	v_cmp_ge_i32_e32 vcc, v4, v12
	v_pk_mul_f32 v[2:3], v[16:17], v[2:3]
	v_cvt_pk_bf16_f32 v0, v5, v19
	v_cndmask_b32_e32 v5, 0, v1, vcc
	v_lshrrev_b32_e32 v1, 16, v1
	v_cmp_ge_i32_e32 vcc, v4, v13
	v_cvt_pk_bf16_f32 v2, v2, v3
	v_pk_mul_f32 v[14:15], v[22:23], v[14:15]
	v_cndmask_b32_e32 v1, 0, v1, vcc
	v_cmp_ge_i32_e32 vcc, v4, v10
	v_perm_b32 v1, v1, v5, s94
	s_lshl_b32 s1, s95, 8
	v_cndmask_b32_e32 v3, 0, v2, vcc
	v_lshrrev_b32_e32 v2, 16, v2
	v_cmp_ge_i32_e32 vcc, v4, v11
	s_lshl_b32 s2, s4, 1
	s_add_u32 s4, s26, s2
	v_cndmask_b32_e32 v2, 0, v2, vcc
	v_perm_b32 v2, v2, v3, s94
	v_cvt_pk_bf16_f32 v3, v14, v15
	v_cmp_ge_i32_e32 vcc, v4, v8
	s_addc_u32 s5, s27, 0
	s_lshl_b32 s34, s14, 8
	v_cndmask_b32_e32 v5, 0, v3, vcc
	v_lshrrev_b32_e32 v3, 16, v3
	v_cmp_ge_i32_e32 vcc, v4, v9
	s_lshl_b32 s2, s0, 1
	s_add_u32 s84, s22, s2
	v_cndmask_b32_e32 v3, 0, v3, vcc
	v_perm_b32 v3, v3, v5, s94
	v_ashrrev_i32_e32 v5, 31, v4
	v_lshlrev_b64 v[4:5], 8, v[4:5]
	v_lshl_add_u64 v[4:5], v[6:7], 0, v[4:5]
	global_store_dwordx4 v[4:5], v[0:3], off
	s_addc_u32 s85, s23, 0
	s_mov_b32 s14, 0
	v_ashrrev_i32_e32 v1, 1, v18
	v_lshrrev_b32_e32 v2, 2, v18
	v_ashrrev_i32_e32 v0, 4, v18
	v_and_b32_e32 v1, 0xffffffc0, v1
	v_and_b32_e32 v2, 12, v2
	v_or3_b32 v111, v2, v1, 1
	v_add_u32_e32 v2, 16, v0
	v_ashrrev_i32_e32 v3, 31, v2
	v_lshl_add_u64 v[70:71], s[8:9], 0, v[2:3]
	v_add_u32_e32 v2, 32, v0
	v_ashrrev_i32_e32 v3, 31, v2
	v_lshl_add_u64 v[72:73], s[8:9], 0, v[2:3]
	v_add_u32_e32 v2, 48, v0
	v_ashrrev_i32_e32 v3, 31, v2
	v_lshl_add_u64 v[74:75], s[8:9], 0, v[2:3]
	v_add_u32_e32 v2, 64, v0
	v_ashrrev_i32_e32 v3, 31, v2
	v_lshlrev_b32_e32 v1, 3, v18
	v_lshl_add_u64 v[76:77], s[8:9], 0, v[2:3]
	v_add_u32_e32 v2, 0x50, v0
	v_and_b32_e32 v110, 0x78, v1
	v_ashrrev_i32_e32 v1, 31, v0
	v_ashrrev_i32_e32 v3, 31, v2
	v_mul_lo_u32 v5, v0, s93
	v_lshl_add_u64 v[68:69], s[8:9], 0, v[0:1]
	v_lshl_add_u64 v[78:79], s[8:9], 0, v[2:3]
	v_add_u32_e32 v2, 0x60, v0
	v_add_u32_e32 v0, 0x70, v0
	v_ashrrev_i32_e32 v3, 31, v2
	v_ashrrev_i32_e32 v1, 31, v0
	v_lshl_add_u32 v4, v110, 2, 0
	v_lshlrev_b32_e32 v64, 1, v110
	v_lshl_add_u64 v[80:81], s[8:9], 0, v[2:3]
	v_lshl_add_u64 v[82:83], s[8:9], 0, v[0:1]
	v_lshl_add_u64 v[88:89], s[84:85], 0, v[64:65]
	v_lshlrev_b64 v[90:91], 11, v[68:69]
	v_lshlrev_b64 v[92:93], 11, v[70:71]
	v_lshlrev_b64 v[94:95], 11, v[72:73]
	v_lshlrev_b64 v[96:97], 11, v[74:75]
	v_lshlrev_b64 v[98:99], 11, v[76:77]
	v_lshlrev_b64 v[100:101], 11, v[78:79]
	v_lshlrev_b64 v[102:103], 11, v[80:81]
	v_lshlrev_b64 v[104:105], 11, v[82:83]
	s_mov_b64 s[8:9], -1
	v_add_u32_e32 v112, v4, v5
	v_mov_b32_e32 v67, v66
	v_mov_b32_e32 v84, v66
	v_mov_b32_e32 v85, v66
	v_mov_b32_e32 v86, v66
	v_mov_b32_e32 v87, v66
	v_mov_b32_e32 v106, v66
	v_mov_b32_e32 v107, v66
	s_waitcnt vmcnt(0)
	v_cmp_gt_u32_e32 vcc, 64, v140
	s_nop 1
	s_and_b64 vcc, exec, vcc
	s_cbranch_vccz .Lmy_pc_noinv
	buffer_inv sc1
	s_waitcnt vmcnt(0)
.Lmy_pc_noinv:
	s_barrier
.LBB0_1690:
	v_mov_b32_e32 v6, v140
	s_or_b32 s84, s14, s1
	v_lshlrev_b32_e32 v0, 4, v6
	v_and_b32_e32 v1, 48, v6
	v_lshlrev_b32_e32 v7, 7, v6
	v_bitop3_b32 v0, v0, v1, s3 bitop3:0x6c
	v_mov_b32_e32 v1, v140
	v_and_or_b32 v113, v7, s35, v0
	s_barrier
	s_ashr_i32 s85, s84, 31
	v_ashrrev_i32_e32 v0, 3, v1
	v_xor_b32_e32 v2, v0, v1
	s_lshl_b64 s[84:85], s[84:85], 9
	v_lshlrev_b32_e32 v2, 4, v2
	s_add_u32 s90, s10, s84
	v_and_b32_e32 v2, 0x70, v2
	s_addc_u32 s91, s11, s85
	v_lshl_or_b32 v64, v0, 11, v2
	v_lshl_or_b32 v0, v0, 9, v2
	v_lshl_add_u32 v8, v1, 4, 0
	v_mov_b32_e32 v1, v65
	v_lshl_add_u64 v[4:5], s[90:91], 0, v[0:1]
	v_add_u32_e32 v1, 0x4000, v8
	v_readfirstlane_b32 s2, v8
	s_mov_b32 m0, s2
	v_readfirstlane_b32 s2, v1
	v_add_u32_e32 v9, 0x1000, v8
	v_lshl_add_u64 v[2:3], s[6:7], 0, v[64:65]
	global_load_lds_dwordx4 v64, s[6:7]
	s_mov_b32 m0, s2
	v_readfirstlane_b32 s2, v9
	v_add_u32_e32 v9, 0x5000, v8
	global_load_lds_dwordx4 v0, s[90:91]
	v_lshl_add_u64 v[0:1], v[2:3], 0, s[16:17]
	s_mov_b32 m0, s2
	v_readfirstlane_b32 s2, v9
	v_add_u32_e32 v9, 0x2000, v8
	global_load_lds_dwordx4 v[0:1], off
	v_lshl_add_u64 v[0:1], v[4:5], 0, s[66:67]
	s_mov_b32 m0, s2
	v_readfirstlane_b32 s2, v9
	v_add_u32_e32 v9, 0x6000, v8
	global_load_lds_dwordx4 v[0:1], off
	v_lshl_add_u64 v[0:1], v[2:3], 0, s[18:19]
	s_mov_b32 m0, s2
	s_mov_b64 s[84:85], 0x8000
	v_readfirstlane_b32 s2, v9
	global_load_lds_dwordx4 v[0:1], off
	v_lshl_add_u64 v[0:1], v[4:5], 0, s[84:85]
	s_mov_b32 m0, s2
	s_mov_b64 s[84:85], 0xc000
	global_load_lds_dwordx4 v[0:1], off
	v_lshl_add_u64 v[0:1], v[2:3], 0, s[20:21]
	v_add_u32_e32 v2, 0x3000, v8
	v_mov_b32_e32 v56, v113
	v_readfirstlane_b32 s2, v2
	v_add_u32_e32 v2, 0x7000, v8
	s_mov_b32 m0, s2
	v_readfirstlane_b32 s2, v2
	global_load_lds_dwordx4 v[0:1], off
	v_lshl_add_u64 v[0:1], v[4:5], 0, s[84:85]
	s_mov_b32 m0, s2
	s_mov_b64 s[84:85], 0x8080
	global_load_lds_dwordx4 v[0:1], off
	v_lshlrev_b32_e32 v0, 6, v6
	v_and_b32_e32 v1, 0x2000, v7
	v_and_b32_e32 v0, 0xffffe000, v0
	v_add_u32_e32 v114, 0, v1
	v_mov_b32_e32 v1, v140
	v_add_u32_e32 v115, 0, v0
	s_waitcnt vmcnt(0) lgkmcnt(0)
	s_barrier
; template <bool SHIFT>
; __device__ __forceinline__ void gemm_issue(const ushort_t* __restrict__ P, int ldp, const ushort_t* __restrict__ Q, int ldq,
;                                            int k0, int grow0, const ushort_t* zrow, char* bufA, char* bufB) {
;     ...
; #pragma unroll
;   for (int i = 0; i < 4; ++i) {
;     const char* src;
;     if (SHIFT && k0 >= 1024) {
;       src = (const char*)P + ((long)(i * 32 - 1) * ldp + (k0 - 1024)) * 2 + voa;
;       if (((grow0 + (tid >> 3) + i * 32) & 4095) == 0) src = (const char*)zrow + sc * 2;
;     } else {
;       src = (const char*)P + ((long)(i * 32) * ldp + k0) * 2 + voa;
;     }
;     __builtin_amdgcn_global_load_lds((const unsigned*)src, (unsigned*)(bufA + tid * 16 + i * 4096), 16, 0, 0);
;     const char* srb = (const char*)Q + ((long)(i * 32) * ldq + k0) * 2 + vob;
;     __builtin_amdgcn_global_load_lds((const unsigned*)srb, (unsigned*)(bufB + tid * 16 + i * 4096), 16, 0, 0);
;   }
;     ...
;   for (int kt0 = 0; kt0 < nk; kt0 += 2) {
; #pragma unroll
;     for (int u = 0; u < 2; ++u) {
;       const int kt = kt0 + u;
;       if (kt < nk) {
;         asm volatile("s_waitcnt vmcnt(0) lgkmcnt(0)" ::: "memory");
;         __builtin_amdgcn_s_barrier();
;         asm volatile("" ::: "memory");
;         if (kt + 1 < nk) gemm_issue<SHIFT>(P, ldp, Q, ldq, (kt + 1) << 6, grow0, zrow, smem + (u ^ 1) * 32768, smem + (u ^ 1) * 32768 + 16384);
;         const char* sA = smem + u * 32768;
;         const char* sB = sA + 16384;
;         int fb = fbase;
;         asm volatile("" : "+v"(fb));
; #pragma unroll
;         for (int ks = 0; ks < 2; ++ks) {
;           bf16x8 a[4], b[4];
;           const int fo = fb ^ (ks << 6);
; #pragma unroll
;           for (int i = 0; i < 4; ++i) a[i] = *(const bf16x8*)(sA + (wp * 64 + i * 16) * 128 + fo);
; #pragma unroll
;           for (int j = 0; j < 4; ++j) b[j] = *(const bf16x8*)(sB + (wq * 64 + j * 16) * 128 + fo);
; #pragma unroll
;           for (int i = 0; i < 4; ++i)
; #pragma unroll
;             for (int j = 0; j < 4; ++j) acc[i][j] = __builtin_amdgcn_mfma_f32_16x16x32_bf16(a[i], b[j], acc[i][j], 0, 0, 0);
;         }
	s_nop 0
	v_ashrrev_i32_e32 v0, 3, v1
	v_xor_b32_e32 v2, v0, v1
	v_lshlrev_b32_e32 v2, 4, v2
	v_and_b32_e32 v2, 0x70, v2
	v_lshl_add_u32 v6, v1, 4, 0
	v_lshl_or_b32 v64, v0, 11, v2
	v_add_u32_e32 v7, 0x8000, v6
	v_lshl_or_b32 v0, v0, 9, v2
	v_lshl_add_u64 v[2:3], s[6:7], 0, v[64:65]
	v_mov_b32_e32 v1, v65
	v_add_u32_e32 v8, 0xc000, v6
	v_readfirstlane_b32 s2, v7
	v_lshl_add_u64 v[0:1], s[90:91], 0, v[0:1]
	v_lshl_add_u64 v[4:5], v[2:3], 0, s[36:37]
	s_mov_b32 m0, s2
	v_readfirstlane_b32 s2, v8
	v_add_u32_e32 v7, 0x9000, v6
	global_load_lds_dwordx4 v[4:5], off
	v_lshl_add_u64 v[4:5], v[0:1], 0, s[36:37]
	s_mov_b32 m0, s2
	v_readfirstlane_b32 s2, v7
	v_add_u32_e32 v7, 0xd000, v6
	global_load_lds_dwordx4 v[4:5], off
	v_lshl_add_u64 v[4:5], v[2:3], 0, s[44:45]
	s_mov_b32 m0, s2
	v_readfirstlane_b32 s2, v7
	v_add_u32_e32 v7, 0xa000, v6
	global_load_lds_dwordx4 v[4:5], off
	v_lshl_add_u64 v[4:5], v[0:1], 0, s[68:69]
	s_mov_b32 m0, s2
	v_readfirstlane_b32 s2, v7
	v_add_u32_e32 v7, 0xe000, v6
	global_load_lds_dwordx4 v[4:5], off
	v_lshl_add_u64 v[4:5], v[2:3], 0, s[46:47]
	s_mov_b32 m0, s2
	v_readfirstlane_b32 s2, v7
	global_load_lds_dwordx4 v[4:5], off
	v_lshl_add_u64 v[4:5], v[0:1], 0, s[84:85]
	s_mov_b32 m0, s2
	v_lshl_add_u64 v[2:3], v[2:3], 0, s[48:49]
	global_load_lds_dwordx4 v[4:5], off
	v_add_u32_e32 v4, 0xb000, v6
	s_mov_b64 s[84:85], 0xc080
	v_readfirstlane_b32 s2, v4
	s_mov_b32 m0, s2
	v_lshl_add_u64 v[0:1], v[0:1], 0, s[84:85]
	global_load_lds_dwordx4 v[2:3], off
	v_add_u32_e32 v2, 0xf000, v6
	s_mov_b64 s[84:85], 0x4100
	v_readfirstlane_b32 s2, v2
	s_mov_b32 m0, s2
	s_nop 0
	global_load_lds_dwordx4 v[0:1], off
	s_nop 0
	v_add_u32_e32 v12, v115, v56
	v_add_u32_e32 v28, v114, v56
	ds_read_b128 v[0:3], v12
	ds_read_b128 v[4:7], v12 offset:2048
	ds_read_b128 v[8:11], v12 offset:4096
	ds_read_b128 v[12:15], v12 offset:6144
	ds_read_b128 v[16:19], v28 offset:16384
	ds_read_b128 v[20:23], v28 offset:18432
	ds_read_b128 v[24:27], v28 offset:20480
	ds_read_b128 v[28:31], v28 offset:22528
	s_waitcnt lgkmcnt(0)
	v_mfma_f32_16x16x32_bf16 v[32:35], v[0:3], v[16:19], 0
	v_mfma_f32_16x16x32_bf16 v[36:39], v[0:3], v[20:23], 0
	v_mfma_f32_16x16x32_bf16 v[40:43], v[0:3], v[24:27], 0
	v_mfma_f32_16x16x32_bf16 v[44:47], v[0:3], v[28:31], 0
	v_xor_b32_e32 v0, 64, v56
	v_add_u32_e32 v1, v115, v0
	v_add_u32_e32 v0, v114, v0
	v_mfma_f32_16x16x32_bf16 v[48:51], v[4:7], v[16:19], 0
	v_mfma_f32_16x16x32_bf16 v[52:55], v[4:7], v[20:23], 0
	v_mfma_f32_16x16x32_bf16 v[116:119], v[4:7], v[24:27], 0
	v_mfma_f32_16x16x32_bf16 v[120:123], v[4:7], v[28:31], 0
	v_mfma_f32_16x16x32_bf16 v[128:131], v[8:11], v[20:23], 0
	v_mfma_f32_16x16x32_bf16 v[146:149], v[12:15], v[20:23], 0
	ds_read_b128 v[4:7], v1
	ds_read_b128 v[20:23], v1 offset:2048
	ds_read_b128 v[158:161], v1 offset:4096
	ds_read_b128 v[162:165], v1 offset:6144
	ds_read_b128 v[166:169], v0 offset:16384
	ds_read_b128 v[170:173], v0 offset:18432
	ds_read_b128 v[174:177], v0 offset:20480
	ds_read_b128 v[178:181], v0 offset:22528
	s_waitcnt vmcnt(0) lgkmcnt(0)
	v_mfma_f32_16x16x32_bf16 v[124:127], v[8:11], v[16:19], 0
	s_barrier
	v_mfma_f32_16x16x32_bf16 v[142:145], v[12:15], v[16:19], 0
	s_waitcnt lgkmcnt(0)
	v_mfma_f32_16x16x32_bf16 v[16:19], v[20:23], v[174:177], v[116:119]
	s_nop 2
	v_mov_b32_e32 v117, v140
	v_mfma_f32_16x16x32_bf16 v[132:135], v[8:11], v[24:27], 0
	v_ashrrev_i32_e32 v116, 3, v117
	v_xor_b32_e32 v64, v116, v117
	v_lshlrev_b32_e32 v64, 4, v64
	v_and_b32_e32 v118, 0x70, v64
	v_lshl_or_b32 v64, v116, 11, v118
	v_lshl_or_b32 v116, v116, 9, v118
	v_lshl_add_u64 v[118:119], s[6:7], 0, v[64:65]
	v_lshl_add_u32 v64, v117, 4, 0
	v_mfma_f32_16x16x32_bf16 v[136:139], v[8:11], v[28:31], 0
	v_mov_b32_e32 v117, v65
	v_readfirstlane_b32 s2, v64
	v_lshl_add_u64 v[116:117], s[90:91], 0, v[116:117]
	v_mfma_f32_16x16x32_bf16 v[150:153], v[12:15], v[24:27], 0
	s_mov_b32 m0, s2
	v_mfma_f32_16x16x32_bf16 v[154:157], v[12:15], v[28:31], 0
	v_mfma_f32_16x16x32_bf16 v[8:11], v[20:23], v[166:169], v[48:51]
	v_mfma_f32_16x16x32_bf16 v[12:15], v[20:23], v[170:173], v[52:55]
	v_mfma_f32_16x16x32_bf16 v[20:23], v[20:23], v[178:181], v[120:123]
	s_nop 2
	v_add_u32_e32 v122, 0x4000, v64
	v_lshl_add_u64 v[120:121], v[118:119], 0, s[50:51]
	v_readfirstlane_b32 s2, v122
	v_add_u32_e32 v122, 0x1000, v64
	global_load_lds_dwordx4 v[120:121], off
	v_lshl_add_u64 v[120:121], v[116:117], 0, s[50:51]
	s_mov_b32 m0, s2
	v_readfirstlane_b32 s2, v122
	v_add_u32_e32 v122, 0x5000, v64
	global_load_lds_dwordx4 v[120:121], off
	v_lshl_add_u64 v[120:121], v[118:119], 0, s[52:53]
	s_mov_b32 m0, s2
	v_readfirstlane_b32 s2, v122
	v_add_u32_e32 v122, 0x2000, v64
	global_load_lds_dwordx4 v[120:121], off
	v_lshl_add_u64 v[120:121], v[116:117], 0, s[84:85]
	s_mov_b32 m0, s2
	v_readfirstlane_b32 s2, v122
	v_add_u32_e32 v122, 0x6000, v64
	global_load_lds_dwordx4 v[120:121], off
	v_lshl_add_u64 v[120:121], v[118:119], 0, s[54:55]
	s_mov_b32 m0, s2
	s_mov_b64 s[84:85], 0x8100
	v_readfirstlane_b32 s2, v122
	global_load_lds_dwordx4 v[120:121], off
	v_lshl_add_u64 v[120:121], v[116:117], 0, s[84:85]
	s_mov_b32 m0, s2
	v_lshl_add_u64 v[118:119], v[118:119], 0, s[56:57]
	global_load_lds_dwordx4 v[120:121], off
	v_add_u32_e32 v120, 0x3000, v64
	v_add_u32_e32 v64, 0x7000, v64
	v_readfirstlane_b32 s2, v120
	s_mov_b32 m0, s2
	s_mov_b64 s[84:85], 0xc100
	v_readfirstlane_b32 s2, v64
	global_load_lds_dwordx4 v[118:119], off
	v_lshl_add_u64 v[116:117], v[116:117], 0, s[84:85]
	s_mov_b32 m0, s2
	v_mov_b32_e32 v64, v113
	v_mfma_f32_16x16x32_bf16 v[28:31], v[158:161], v[170:173], v[128:131]
	global_load_lds_dwordx4 v[116:117], off
	v_mfma_f32_16x16x32_bf16 v[60:63], v[4:7], v[166:169], v[32:35]
	s_nop 0
	v_add_u32_e32 v128, v115, v64
	v_add_u32_e32 v141, v114, v64
	s_mov_b64 s[84:85], 0x4180
	v_mfma_f32_16x16x32_bf16 v[56:59], v[4:7], v[170:173], v[36:39]
	v_mfma_f32_16x16x32_bf16 v[0:3], v[4:7], v[174:177], v[40:43]
	v_mfma_f32_16x16x32_bf16 v[4:7], v[4:7], v[178:181], v[44:47]
	v_mfma_f32_16x16x32_bf16 v[24:27], v[158:161], v[166:169], v[124:127]
	ds_read_b128 v[116:119], v128 offset:32768
	ds_read_b128 v[120:123], v128 offset:34816
	s_nop 0
	ds_read_b128 v[124:127], v128 offset:36864
	ds_read_b128 v[128:131], v128 offset:38912
	v_mfma_f32_16x16x32_bf16 v[32:35], v[158:161], v[174:177], v[132:135]
	v_mfma_f32_16x16x32_bf16 v[36:39], v[158:161], v[178:181], v[136:139]
	v_mfma_f32_16x16x32_bf16 v[40:43], v[162:165], v[166:169], v[142:145]
	v_mfma_f32_16x16x32_bf16 v[44:47], v[162:165], v[170:173], v[146:149]
	ds_read_b128 v[132:135], v141 offset:49152
	ds_read_b128 v[136:139], v141 offset:51200
	ds_read_b128 v[142:145], v141 offset:53248
	ds_read_b128 v[146:149], v141 offset:55296
	v_mfma_f32_16x16x32_bf16 v[48:51], v[162:165], v[174:177], v[150:153]
	v_mfma_f32_16x16x32_bf16 v[52:55], v[162:165], v[178:181], v[154:157]
	s_waitcnt lgkmcnt(0)
; template <bool SHIFT>
; __device__ __forceinline__ void gemm_issue(const ushort_t* __restrict__ P, int ldp, const ushort_t* __restrict__ Q, int ldq,
;                                            int k0, int grow0, const ushort_t* zrow, char* bufA, char* bufB) {
;     ...
; #pragma unroll
;   for (int i = 0; i < 4; ++i) {
;     const char* src;
;     if (SHIFT && k0 >= 1024) {
;       src = (const char*)P + ((long)(i * 32 - 1) * ldp + (k0 - 1024)) * 2 + voa;
;       if (((grow0 + (tid >> 3) + i * 32) & 4095) == 0) src = (const char*)zrow + sc * 2;
;     } else {
;       src = (const char*)P + ((long)(i * 32) * ldp + k0) * 2 + voa;
;     }
;     __builtin_amdgcn_global_load_lds((const unsigned*)src, (unsigned*)(bufA + tid * 16 + i * 4096), 16, 0, 0);
;     const char* srb = (const char*)Q + ((long)(i * 32) * ldq + k0) * 2 + vob;
;     __builtin_amdgcn_global_load_lds((const unsigned*)srb, (unsigned*)(bufB + tid * 16 + i * 4096), 16, 0, 0);
;   }
;     ...
;   for (int kt0 = 0; kt0 < nk; kt0 += 2) {
; #pragma unroll
;     for (int u = 0; u < 2; ++u) {
;       const int kt = kt0 + u;
;       if (kt < nk) {
;         asm volatile("s_waitcnt vmcnt(0) lgkmcnt(0)" ::: "memory");
;         __builtin_amdgcn_s_barrier();
;         asm volatile("" ::: "memory");
;         if (kt + 1 < nk) gemm_issue<SHIFT>(P, ldp, Q, ldq, (kt + 1) << 6, grow0, zrow, smem + (u ^ 1) * 32768, smem + (u ^ 1) * 32768 + 16384);
;         const char* sA = smem + u * 32768;
;         const char* sB = sA + 16384;
;         int fb = fbase;
;         asm volatile("" : "+v"(fb));
; #pragma unroll
;         for (int ks = 0; ks < 2; ++ks) {
;           bf16x8 a[4], b[4];
;           const int fo = fb ^ (ks << 6);
; #pragma unroll
;           for (int i = 0; i < 4; ++i) a[i] = *(const bf16x8*)(sA + (wp * 64 + i * 16) * 128 + fo);
; #pragma unroll
;           for (int j = 0; j < 4; ++j) b[j] = *(const bf16x8*)(sB + (wq * 64 + j * 16) * 128 + fo);
; #pragma unroll
;           for (int i = 0; i < 4; ++i)
; #pragma unroll
;             for (int j = 0; j < 4; ++j) acc[i][j] = __builtin_amdgcn_mfma_f32_16x16x32_bf16(a[i], b[j], acc[i][j], 0, 0, 0);
;         }
	v_mfma_f32_16x16x32_bf16 v[150:153], v[116:119], v[142:145], v[0:3]
	s_nop 2
	v_xor_b32_e32 v0, 64, v64
	v_add_u32_e32 v1, v115, v0
	v_add_u32_e32 v0, v114, v0
	v_mfma_f32_16x16x32_bf16 v[60:63], v[116:119], v[132:135], v[60:63]
	v_mfma_f32_16x16x32_bf16 v[56:59], v[116:119], v[136:139], v[56:59]
	v_mfma_f32_16x16x32_bf16 v[116:119], v[116:119], v[146:149], v[4:7]
	v_mfma_f32_16x16x32_bf16 v[154:157], v[120:123], v[132:135], v[8:11]
	v_mfma_f32_16x16x32_bf16 v[158:161], v[120:123], v[136:139], v[12:15]
	v_mfma_f32_16x16x32_bf16 v[162:165], v[120:123], v[142:145], v[16:19]
	v_mfma_f32_16x16x32_bf16 v[120:123], v[120:123], v[146:149], v[20:23]
	v_mfma_f32_16x16x32_bf16 v[166:169], v[124:127], v[132:135], v[24:27]
	v_mfma_f32_16x16x32_bf16 v[170:173], v[124:127], v[136:139], v[28:31]
	v_mfma_f32_16x16x32_bf16 v[174:177], v[124:127], v[142:145], v[32:35]
	v_mfma_f32_16x16x32_bf16 v[124:127], v[124:127], v[146:149], v[36:39]
	v_mfma_f32_16x16x32_bf16 v[132:135], v[128:131], v[132:135], v[40:43]
	v_mfma_f32_16x16x32_bf16 v[136:139], v[128:131], v[136:139], v[44:47]
	v_mfma_f32_16x16x32_bf16 v[142:145], v[128:131], v[142:145], v[48:51]
	v_mfma_f32_16x16x32_bf16 v[128:131], v[128:131], v[146:149], v[52:55]
	ds_read_b128 v[12:15], v1 offset:32768
	ds_read_b128 v[28:31], v1 offset:34816
	ds_read_b128 v[44:47], v1 offset:36864
	ds_read_b128 v[146:149], v1 offset:38912
	ds_read_b128 v[48:51], v0 offset:49152
	ds_read_b128 v[52:55], v0 offset:51200
	ds_read_b128 v[178:181], v0 offset:53248
	ds_read_b128 v[182:185], v0 offset:55296
	s_waitcnt vmcnt(0) lgkmcnt(0)
	s_waitcnt lgkmcnt(0)
	v_mfma_f32_16x16x32_bf16 v[0:3], v[12:15], v[48:51], v[60:63]
	s_barrier
	v_mfma_f32_16x16x32_bf16 v[4:7], v[12:15], v[52:55], v[56:59]
	v_mfma_f32_16x16x32_bf16 v[8:11], v[12:15], v[178:181], v[150:153]
	v_mfma_f32_16x16x32_bf16 v[12:15], v[12:15], v[182:185], v[116:119]
	s_nop 2
	v_mov_b32_e32 v117, v140
	v_mfma_f32_16x16x32_bf16 v[16:19], v[28:31], v[48:51], v[154:157]
	v_ashrrev_i32_e32 v116, 3, v117
	v_xor_b32_e32 v64, v116, v117
	v_lshlrev_b32_e32 v64, 4, v64
	v_and_b32_e32 v118, 0x70, v64
	v_lshl_or_b32 v64, v116, 11, v118
	v_lshl_or_b32 v116, v116, 9, v118
	v_lshl_add_u64 v[118:119], s[6:7], 0, v[64:65]
	v_lshl_add_u32 v64, v117, 4, 0
	v_mfma_f32_16x16x32_bf16 v[20:23], v[28:31], v[52:55], v[158:161]
	v_mov_b32_e32 v117, v65
	v_lshl_add_u64 v[116:117], s[90:91], 0, v[116:117]
	v_mfma_f32_16x16x32_bf16 v[24:27], v[28:31], v[178:181], v[162:165]
	v_mfma_f32_16x16x32_bf16 v[28:31], v[28:31], v[182:185], v[120:123]
	s_nop 2
	v_add_u32_e32 v122, 0x8000, v64
	v_add_u32_e32 v123, 0xc000, v64
	v_readfirstlane_b32 s2, v122
	v_lshl_add_u64 v[120:121], v[118:119], 0, s[58:59]
	s_mov_b32 m0, s2
	v_readfirstlane_b32 s2, v123
	v_add_u32_e32 v122, 0x9000, v64
	global_load_lds_dwordx4 v[120:121], off
	v_lshl_add_u64 v[120:121], v[116:117], 0, s[58:59]
	s_mov_b32 m0, s2
	v_readfirstlane_b32 s2, v122
	v_add_u32_e32 v122, 0xd000, v64
	global_load_lds_dwordx4 v[120:121], off
	v_lshl_add_u64 v[120:121], v[118:119], 0, s[60:61]
	s_mov_b32 m0, s2
	v_readfirstlane_b32 s2, v122
	v_add_u32_e32 v122, 0xa000, v64
	global_load_lds_dwordx4 v[120:121], off
	v_lshl_add_u64 v[120:121], v[116:117], 0, s[84:85]
	s_mov_b32 m0, s2
	v_readfirstlane_b32 s2, v122
	v_add_u32_e32 v122, 0xe000, v64
	global_load_lds_dwordx4 v[120:121], off
	v_lshl_add_u64 v[120:121], v[118:119], 0, s[62:63]
	s_mov_b32 m0, s2
	s_mov_b64 s[84:85], 0x8180
	v_readfirstlane_b32 s2, v122
	global_load_lds_dwordx4 v[120:121], off
	v_lshl_add_u64 v[120:121], v[116:117], 0, s[84:85]
	s_mov_b32 m0, s2
	v_lshl_add_u64 v[118:119], v[118:119], 0, s[64:65]
	global_load_lds_dwordx4 v[120:121], off
	v_add_u32_e32 v120, 0xb000, v64
	v_add_u32_e32 v64, 0xf000, v64
	v_readfirstlane_b32 s2, v120
	s_mov_b32 m0, s2
	s_mov_b64 s[84:85], 0xc180
	v_readfirstlane_b32 s2, v64
	global_load_lds_dwordx4 v[118:119], off
	v_lshl_add_u64 v[116:117], v[116:117], 0, s[84:85]
	s_mov_b32 m0, s2
	v_mov_b32_e32 v64, v113
	v_mfma_f32_16x16x32_bf16 v[60:63], v[146:149], v[182:185], v[128:131]
	global_load_lds_dwordx4 v[116:117], off
	v_mfma_f32_16x16x32_bf16 v[32:35], v[44:47], v[48:51], v[166:169]
	s_nop 0
	v_add_u32_e32 v128, v115, v64
	v_add_u32_e32 v141, v114, v64
	v_xor_b32_e32 v64, 64, v64
	v_mfma_f32_16x16x32_bf16 v[36:39], v[44:47], v[52:55], v[170:173]
	s_or_b32 s84, s14, s34
	s_ashr_i32 s85, s84, 31
	s_lshl_b64 s[84:85], s[84:85], 13
	v_mfma_f32_16x16x32_bf16 v[40:43], v[44:47], v[178:181], v[174:177]
	s_add_u32 s90, s4, s84
	s_addc_u32 s91, s5, s85
	s_mov_b64 s[84:85], 0x2000
	v_mfma_f32_16x16x32_bf16 v[44:47], v[44:47], v[182:185], v[124:127]
	ds_read_b128 v[116:119], v128
	ds_read_b128 v[120:123], v128 offset:2048
	s_nop 0
	ds_read_b128 v[124:127], v128 offset:4096
	ds_read_b128 v[128:131], v128 offset:6144
	s_and_b64 vcc, exec, s[8:9]
	s_mov_b64 s[8:9], 0
	v_mfma_f32_16x16x32_bf16 v[48:51], v[146:149], v[48:51], v[132:135]
	v_mfma_f32_16x16x32_bf16 v[52:55], v[146:149], v[52:55], v[136:139]
	v_mfma_f32_16x16x32_bf16 v[56:59], v[146:149], v[178:181], v[142:145]
	s_nop 0
	ds_read_b128 v[132:135], v141 offset:16384
	ds_read_b128 v[136:139], v141 offset:18432
	ds_read_b128 v[142:145], v141 offset:20480
	ds_read_b128 v[146:149], v141 offset:22528
	s_waitcnt lgkmcnt(0)
	v_mfma_f32_16x16x32_bf16 v[48:51], v[128:131], v[132:135], v[48:51]
	v_mfma_f32_16x16x32_bf16 v[52:55], v[128:131], v[136:139], v[52:55]
	v_mfma_f32_16x16x32_bf16 v[56:59], v[128:131], v[142:145], v[56:59]
	v_mfma_f32_16x16x32_bf16 v[60:63], v[128:131], v[146:149], v[60:63]
	v_add_u32_e32 v128, v115, v64
	v_add_u32_e32 v64, v114, v64
	v_mfma_f32_16x16x32_bf16 v[0:3], v[116:119], v[132:135], v[0:3]
	v_mfma_f32_16x16x32_bf16 v[4:7], v[116:119], v[136:139], v[4:7]
	v_mfma_f32_16x16x32_bf16 v[8:11], v[116:119], v[142:145], v[8:11]
	v_mfma_f32_16x16x32_bf16 v[12:15], v[116:119], v[146:149], v[12:15]
	v_mfma_f32_16x16x32_bf16 v[16:19], v[120:123], v[132:135], v[16:19]
	v_mfma_f32_16x16x32_bf16 v[20:23], v[120:123], v[136:139], v[20:23]
	v_mfma_f32_16x16x32_bf16 v[24:27], v[120:123], v[142:145], v[24:27]
	v_mfma_f32_16x16x32_bf16 v[28:31], v[120:123], v[146:149], v[28:31]
	v_mfma_f32_16x16x32_bf16 v[32:35], v[124:127], v[132:135], v[32:35]
	v_mfma_f32_16x16x32_bf16 v[36:39], v[124:127], v[136:139], v[36:39]
	v_mfma_f32_16x16x32_bf16 v[40:43], v[124:127], v[142:145], v[40:43]
	v_mfma_f32_16x16x32_bf16 v[44:47], v[124:127], v[146:149], v[44:47]
	ds_read_b128 v[116:119], v128
	ds_read_b128 v[120:123], v128 offset:2048
	ds_read_b128 v[124:127], v128 offset:4096
	ds_read_b128 v[128:131], v128 offset:6144
	ds_read_b128 v[132:135], v64 offset:16384
	ds_read_b128 v[136:139], v64 offset:18432
	ds_read_b128 v[142:145], v64 offset:20480
	ds_read_b128 v[146:149], v64 offset:22528
	s_waitcnt vmcnt(0) lgkmcnt(0)
	s_barrier
;     ...
;         for (int ks = 0; ks < 2; ++ks) {
;           bf16x8 a[4], b[4];
;           const int fo = fb ^ (ks << 6);
; #pragma unroll
;           for (int i = 0; i < 4; ++i) a[i] = *(const bf16x8*)(sA + (wp * 64 + i * 16) * 128 + fo);
; #pragma unroll
;           for (int j = 0; j < 4; ++j) b[j] = *(const bf16x8*)(sB + (wq * 64 + j * 16) * 128 + fo);
; #pragma unroll
;           for (int i = 0; i < 4; ++i)
; #pragma unroll
;             for (int j = 0; j < 4; ++j) acc[i][j] = __builtin_amdgcn_mfma_f32_16x16x32_bf16(a[i], b[j], acc[i][j], 0, 0, 0);
; __device__ __forceinline__ void phase_ret_passC(const Params& p, char* smem) {
;     ...
;       int nb = wp * 64 + g * 4 + 1;
;       asm volatile("" : "+v"(nb));
; #pragma unroll
;       for (int i = 0; i < 4; ++i)
; #pragma unroll
;         for (int r = 0; r < 4; ++r) {
;           const float xi = __builtin_amdgcn_exp2f((float)(nb + i * 16 + r) * l2g);
; #pragma unroll
;           for (int j = 0; j < 4; ++j) acc[i][j][r] *= xi;
;         }
	s_waitcnt lgkmcnt(0)
	v_mfma_f32_16x16x32_bf16 v[0:3], v[116:119], v[132:135], v[0:3]
	v_add_u32_e32 v64, v115, v113
	v_mfma_f32_16x16x32_bf16 v[4:7], v[116:119], v[136:139], v[4:7]
	v_mfma_f32_16x16x32_bf16 v[8:11], v[116:119], v[142:145], v[8:11]
	v_mfma_f32_16x16x32_bf16 v[12:15], v[116:119], v[146:149], v[12:15]
	v_mfma_f32_16x16x32_bf16 v[16:19], v[120:123], v[132:135], v[16:19]
	v_mfma_f32_16x16x32_bf16 v[20:23], v[120:123], v[136:139], v[20:23]
	v_mfma_f32_16x16x32_bf16 v[24:27], v[120:123], v[142:145], v[24:27]
	v_mfma_f32_16x16x32_bf16 v[28:31], v[120:123], v[146:149], v[28:31]
	v_mfma_f32_16x16x32_bf16 v[32:35], v[124:127], v[132:135], v[32:35]
	v_mfma_f32_16x16x32_bf16 v[36:39], v[124:127], v[136:139], v[36:39]
	v_mfma_f32_16x16x32_bf16 v[40:43], v[124:127], v[142:145], v[40:43]
	v_mfma_f32_16x16x32_bf16 v[44:47], v[124:127], v[146:149], v[44:47]
	v_mfma_f32_16x16x32_bf16 v[48:51], v[128:131], v[132:135], v[48:51]
	v_mfma_f32_16x16x32_bf16 v[52:55], v[128:131], v[136:139], v[52:55]
	v_mfma_f32_16x16x32_bf16 v[56:59], v[128:131], v[142:145], v[56:59]
	v_mfma_f32_16x16x32_bf16 v[60:63], v[128:131], v[146:149], v[60:63]
	ds_read_b128 v[116:119], v64 offset:32768
	ds_read_b128 v[120:123], v64 offset:34816
	ds_read_b128 v[124:127], v64 offset:36864
	ds_read_b128 v[128:131], v64 offset:38912
	v_add_u32_e32 v64, v114, v113
	ds_read_b128 v[132:135], v64 offset:49152
	ds_read_b128 v[136:139], v64 offset:51200
	ds_read_b128 v[142:145], v64 offset:53248
	ds_read_b128 v[146:149], v64 offset:55296
	v_xor_b32_e32 v64, 64, v113
	v_add_u32_e32 v113, v115, v64
	v_add_u32_e32 v64, v114, v64
	s_waitcnt lgkmcnt(0)
	v_mfma_f32_16x16x32_bf16 v[0:3], v[116:119], v[132:135], v[0:3]
	v_mfma_f32_16x16x32_bf16 v[4:7], v[116:119], v[136:139], v[4:7]
	v_mfma_f32_16x16x32_bf16 v[8:11], v[116:119], v[142:145], v[8:11]
	v_mfma_f32_16x16x32_bf16 v[12:15], v[116:119], v[146:149], v[12:15]
	v_mfma_f32_16x16x32_bf16 v[16:19], v[120:123], v[132:135], v[16:19]
	v_mfma_f32_16x16x32_bf16 v[20:23], v[120:123], v[136:139], v[20:23]
	v_mfma_f32_16x16x32_bf16 v[24:27], v[120:123], v[142:145], v[24:27]
	v_mfma_f32_16x16x32_bf16 v[28:31], v[120:123], v[146:149], v[28:31]
	v_mfma_f32_16x16x32_bf16 v[32:35], v[124:127], v[132:135], v[32:35]
	v_mfma_f32_16x16x32_bf16 v[36:39], v[124:127], v[136:139], v[36:39]
	v_mfma_f32_16x16x32_bf16 v[40:43], v[124:127], v[142:145], v[40:43]
	v_mfma_f32_16x16x32_bf16 v[44:47], v[124:127], v[146:149], v[44:47]
	v_mfma_f32_16x16x32_bf16 v[48:51], v[128:131], v[132:135], v[48:51]
	v_mfma_f32_16x16x32_bf16 v[52:55], v[128:131], v[136:139], v[52:55]
	v_mfma_f32_16x16x32_bf16 v[56:59], v[128:131], v[142:145], v[56:59]
	v_mfma_f32_16x16x32_bf16 v[60:63], v[128:131], v[146:149], v[60:63]
	ds_read_b128 v[116:119], v113 offset:32768
	ds_read_b128 v[120:123], v113 offset:34816
	ds_read_b128 v[124:127], v113 offset:36864
	ds_read_b128 v[128:131], v113 offset:38912
	ds_read_b128 v[132:135], v64 offset:49152
	ds_read_b128 v[136:139], v64 offset:51200
	ds_read_b128 v[142:145], v64 offset:53248
	ds_read_b128 v[146:149], v64 offset:55296
	v_mov_b32_e32 v64, v111
	s_waitcnt lgkmcnt(0)
	v_mfma_f32_16x16x32_bf16 v[0:3], v[116:119], v[132:135], v[0:3]
	s_waitcnt vmcnt(0)
	s_barrier
	v_mfma_f32_16x16x32_bf16 v[4:7], v[116:119], v[136:139], v[4:7]
	v_mfma_f32_16x16x32_bf16 v[8:11], v[116:119], v[142:145], v[8:11]
	v_mfma_f32_16x16x32_bf16 v[12:15], v[116:119], v[146:149], v[12:15]
	v_mfma_f32_16x16x32_bf16 v[114:117], v[124:127], v[136:139], v[36:39]
	s_nop 2
	v_add_u32_e32 v37, 1, v64
	v_cvt_f32_i32_e32 v36, v64
	v_cvt_f32_i32_e32 v37, v37
	v_mfma_f32_16x16x32_bf16 v[16:19], v[120:123], v[132:135], v[16:19]
	v_add_u32_e32 v38, 2, v64
	v_mul_f32_e32 v36, v109, v36
	v_mul_f32_e32 v37, v109, v37
	v_exp_f32_e32 v36, v36
	v_exp_f32_e32 v37, v37
	v_mfma_f32_16x16x32_bf16 v[20:23], v[120:123], v[136:139], v[20:23]
	v_add_u32_e32 v39, 3, v64
	v_cvt_f32_i32_e32 v38, v38
	v_cvt_f32_i32_e32 v39, v39
	v_mfma_f32_16x16x32_bf16 v[24:27], v[120:123], v[142:145], v[24:27]
	v_mul_f32_e32 v38, v109, v38
	v_mul_f32_e32 v39, v109, v39
	v_mfma_f32_16x16x32_bf16 v[28:31], v[120:123], v[146:149], v[28:31]
	v_exp_f32_e32 v38, v38
	v_exp_f32_e32 v39, v39
	v_mfma_f32_16x16x32_bf16 v[32:35], v[124:127], v[132:135], v[32:35]
	v_mfma_f32_16x16x32_bf16 v[118:121], v[124:127], v[142:145], v[40:43]
	v_mfma_f32_16x16x32_bf16 v[122:125], v[124:127], v[146:149], v[44:47]
	v_mfma_f32_16x16x32_bf16 v[132:135], v[128:131], v[132:135], v[48:51]
	s_nop 1
	v_mul_f32_e64 v44, v12, v36
	v_mul_f32_e64 v45, v13, v37
	v_pk_mul_f32 v[46:47], v[14:15], v[38:39]
	v_mfma_f32_16x16x32_bf16 v[136:139], v[128:131], v[136:139], v[52:55]
	v_mfma_f32_16x16x32_bf16 v[142:145], v[128:131], v[142:145], v[56:59]
	s_nop 1
	v_mul_f32_e64 v52, v8, v36
	v_mul_f32_e64 v53, v9, v37
	v_pk_mul_f32 v[54:55], v[10:11], v[38:39]
	v_mfma_f32_16x16x32_bf16 v[126:129], v[128:131], v[146:149], v[60:63]
	v_mul_f32_e64 v56, v4, v36
	v_mul_f32_e64 v57, v5, v37
	v_pk_mul_f32 v[58:59], v[6:7], v[38:39]
	v_pk_mul_f32 v[60:61], v[0:1], v[36:37]
	v_add_u32_e32 v0, 16, v64
	v_add_u32_e32 v1, 17, v64
	v_cvt_f32_i32_e32 v0, v0
	v_cvt_f32_i32_e32 v1, v1
	v_pk_mul_f32 v[62:63], v[2:3], v[38:39]
	v_add_u32_e32 v2, 18, v64
	v_mul_f32_e32 v0, v109, v0
	v_mul_f32_e32 v1, v109, v1
	v_exp_f32_e32 v0, v0
	v_exp_f32_e32 v1, v1
	v_add_u32_e32 v3, 19, v64
	v_cvt_f32_i32_e32 v2, v2
	v_cvt_f32_i32_e32 v3, v3
	v_pk_mul_f32 v[48:49], v[16:17], v[0:1]
	v_pk_mul_f32 v[40:41], v[20:21], v[0:1]
	v_pk_mul_f32 v[36:37], v[24:25], v[0:1]
	v_pk_mul_f32 v[28:29], v[28:29], v[0:1]
	v_add_u32_e32 v0, 32, v64
	v_add_u32_e32 v1, 33, v64
	v_cvt_f32_i32_e32 v0, v0
;     ...
;   __syncthreads();
;   gemm_issue<SHIFT>(P, ldp, Q, ldq, 0, grow0, zrow, smem, smem + 16384);
;   for (int kt0 = 0; kt0 < nk; kt0 += 2) {
; #pragma unroll
;     for (int u = 0; u < 2; ++u) {
;       const int kt = kt0 + u;
;       if (kt < nk) {
;         asm volatile("s_waitcnt vmcnt(0) lgkmcnt(0)" ::: "memory");
;         __builtin_amdgcn_s_barrier();
;         asm volatile("" ::: "memory");
;         if (kt + 1 < nk) gemm_issue<SHIFT>(P, ldp, Q, ldq, (kt + 1) << 6, grow0, zrow, smem + (u ^ 1) * 32768, smem + (u ^ 1) * 32768 + 16384);
; __device__ __forceinline__ void phase_ret_passC(const Params& p, char* smem) {
;     ...
;       int nb = wp * 64 + g * 4 + 1;
;       asm volatile("" : "+v"(nb));
; #pragma unroll
;       for (int i = 0; i < 4; ++i)
; #pragma unroll
;         for (int r = 0; r < 4; ++r) {
;           const float xi = __builtin_amdgcn_exp2f((float)(nb + i * 16 + r) * l2g);
; #pragma unroll
;           for (int j = 0; j < 4; ++j) acc[i][j][r] *= xi;
;         }
;       gemm_core<true, false>(scr, 128, VT + ((long)(bh * 256 + eh * 128)) * 4096 + c * 128, 4096, 128, smem, acc);
	v_cvt_f32_i32_e32 v1, v1
	v_mul_f32_e32 v2, v109, v2
	v_mul_f32_e32 v3, v109, v3
	v_mul_f32_e32 v0, v109, v0
	v_mul_f32_e32 v1, v109, v1
	v_exp_f32_e32 v0, v0
	v_exp_f32_e32 v1, v1
	v_exp_f32_e32 v2, v2
	v_exp_f32_e32 v3, v3
	v_pk_mul_f32 v[32:33], v[32:33], v[0:1]
	v_pk_mul_f32 v[24:25], v[114:115], v[0:1]
	v_pk_mul_f32 v[20:21], v[118:119], v[0:1]
	v_pk_mul_f32 v[12:13], v[122:123], v[0:1]
	v_add_u32_e32 v0, 48, v64
	v_cvt_f32_i32_e32 v0, v0
	v_pk_mul_f32 v[50:51], v[18:19], v[2:3]
	v_pk_mul_f32 v[42:43], v[22:23], v[2:3]
	v_pk_mul_f32 v[38:39], v[26:27], v[2:3]
	v_mul_f32_e32 v0, v109, v0
	v_exp_f32_e32 v8, v0
	v_add_u32_e32 v0, 49, v64
	v_pk_mul_f32 v[30:31], v[30:31], v[2:3]
	v_add_u32_e32 v2, 34, v64
	v_add_u32_e32 v3, 35, v64
	v_cvt_f32_i32_e32 v0, v0
	v_cvt_f32_i32_e32 v2, v2
	v_cvt_f32_i32_e32 v3, v3
	v_mov_b32_e32 v115, v140
	v_mul_f32_e32 v0, v109, v0
	v_mul_f32_e32 v2, v109, v2
	v_mul_f32_e32 v3, v109, v3
	v_exp_f32_e32 v9, v0
	v_add_u32_e32 v0, 50, v64
	v_exp_f32_e32 v2, v2
	v_exp_f32_e32 v3, v3
	v_cvt_f32_i32_e32 v0, v0
	v_pk_mul_f32 v[16:17], v[132:133], v[8:9]
	v_pk_mul_f32 v[4:5], v[142:143], v[8:9]
	v_pk_mul_f32 v[22:23], v[120:121], v[2:3]
	v_mul_f32_e32 v0, v109, v0
	v_mov_b32_e32 v120, v140
	v_exp_f32_e32 v10, v0
	v_add_u32_e32 v0, 51, v64
	s_nop 0
	v_lshlrev_b32_e32 v64, 4, v120
	v_and_b32_e32 v113, 48, v120
	v_lshlrev_b32_e32 v121, 7, v120
	v_bitop3_b32 v64, v64, v113, s3 bitop3:0x6c
	s_barrier
	v_and_or_b32 v113, v121, s35, v64
	v_ashrrev_i32_e32 v114, 3, v115
	v_xor_b32_e32 v64, v114, v115
	v_lshlrev_b32_e32 v64, 4, v64
	v_pk_mul_f32 v[26:27], v[116:117], v[2:3]
	v_and_b32_e32 v116, 0x70, v64
	v_lshl_add_u32 v122, v115, 4, 0
	v_lshl_or_b32 v64, v114, 8, v116
	v_lshl_or_b32 v114, v114, 13, v116
	v_mov_b32_e32 v115, v65
	v_readfirstlane_b32 s2, v122
	v_lshl_add_u64 v[118:119], s[90:91], 0, v[114:115]
	v_add_u32_e32 v115, 0x4000, v122
	s_mov_b32 m0, s2
	v_lshl_add_u64 v[116:117], s[12:13], 0, v[64:65]
	global_load_lds_dwordx4 v64, s[12:13]
	v_readfirstlane_b32 s2, v115
	v_add_u32_e32 v64, 0x1000, v122
	s_mov_b32 m0, s2
	v_readfirstlane_b32 s2, v64
	v_add_u32_e32 v64, 0x5000, v122
	global_load_lds_dwordx4 v114, s[90:91]
	v_lshl_add_u64 v[114:115], v[116:117], 0, s[84:85]
	s_mov_b32 m0, s2
	s_mov_b64 s[84:85], 0x40000
	v_readfirstlane_b32 s2, v64
	v_add_u32_e32 v64, 0x2000, v122
	global_load_lds_dwordx4 v[114:115], off
	v_lshl_add_u64 v[114:115], v[118:119], 0, s[84:85]
	s_mov_b32 m0, s2
	v_readfirstlane_b32 s2, v64
	v_add_u32_e32 v64, 0x6000, v122
	global_load_lds_dwordx4 v[114:115], off
	v_lshl_add_u64 v[114:115], v[116:117], 0, s[66:67]
	s_mov_b32 m0, s2
	s_mov_b64 s[84:85], 0x80000
	v_readfirstlane_b32 s2, v64
	v_add_u32_e32 v64, 0x3000, v122
	global_load_lds_dwordx4 v[114:115], off
	v_lshl_add_u64 v[114:115], v[118:119], 0, s[84:85]
	s_mov_b32 m0, s2
	v_readfirstlane_b32 s2, v64
	v_add_u32_e32 v64, 0x7000, v122
	global_load_lds_dwordx4 v[114:115], off
	v_lshl_add_u64 v[114:115], v[116:117], 0, s[70:71]
	s_mov_b32 m0, s2
	v_readfirstlane_b32 s2, v64
	global_load_lds_dwordx4 v[114:115], off
	v_lshl_add_u64 v[114:115], v[118:119], 0, s[72:73]
	s_mov_b32 m0, s2
	v_mov_b32_e32 v117, v140
	global_load_lds_dwordx4 v[114:115], off
	v_lshlrev_b32_e32 v64, 6, v120
	s_waitcnt vmcnt(0) lgkmcnt(0)
	s_barrier
	v_and_b32_e32 v115, 0xffffe000, v64
	v_ashrrev_i32_e32 v116, 3, v117
	v_xor_b32_e32 v64, v116, v117
	v_lshlrev_b32_e32 v64, 4, v64
	v_and_b32_e32 v118, 0x70, v64
	v_lshl_or_b32 v64, v116, 8, v118
	v_lshl_or_b32 v116, v116, 13, v118
	v_lshl_add_u64 v[118:119], s[12:13], 0, v[64:65]
	v_lshl_add_u32 v64, v117, 4, 0
	v_add_u32_e32 v122, 0x8000, v64
	v_mov_b32_e32 v117, v65
	v_add_u32_e32 v123, 0xc000, v64
	v_readfirstlane_b32 s2, v122
	v_and_b32_e32 v114, 0x2000, v121
	v_lshl_add_u64 v[116:117], s[90:91], 0, v[116:117]
	v_lshl_add_u64 v[120:121], v[118:119], 0, s[36:37]
	s_mov_b32 m0, s2
	v_readfirstlane_b32 s2, v123
	v_add_u32_e32 v122, 0x9000, v64
	v_cvt_f32_i32_e32 v0, v0
	global_load_lds_dwordx4 v[120:121], off
	v_lshl_add_u64 v[120:121], v[116:117], 0, s[36:37]
	s_mov_b32 m0, s2
	v_readfirstlane_b32 s2, v122
	v_add_u32_e32 v122, 0xd000, v64
	global_load_lds_dwordx4 v[120:121], off
	v_lshl_add_u64 v[120:121], v[118:119], 0, s[74:75]
	s_mov_b32 m0, s2
	v_readfirstlane_b32 s2, v122
	v_add_u32_e32 v122, 0xa000, v64
	global_load_lds_dwordx4 v[120:121], off
	v_lshl_add_u64 v[120:121], v[116:117], 0, s[76:77]
	s_mov_b32 m0, s2
	v_readfirstlane_b32 s2, v122
	v_add_u32_e32 v122, 0xe000, v64
	global_load_lds_dwordx4 v[120:121], off
	v_lshl_add_u64 v[120:121], v[118:119], 0, s[68:69]
	s_mov_b32 m0, s2
	v_readfirstlane_b32 s2, v122
	v_mul_f32_e32 v0, v109, v0
	global_load_lds_dwordx4 v[120:121], off
	v_lshl_add_u64 v[120:121], v[116:117], 0, s[78:79]
	s_mov_b32 m0, s2
	v_exp_f32_e32 v11, v0
	global_load_lds_dwordx4 v[120:121], off
	v_add_u32_e32 v120, 0xb000, v64
	v_add_u32_e32 v64, 0xf000, v64
	v_readfirstlane_b32 s2, v120
	v_lshl_add_u64 v[118:119], v[118:119], 0, s[80:81]
	s_mov_b32 m0, s2
	v_readfirstlane_b32 s2, v64
	global_load_lds_dwordx4 v[118:119], off
	v_lshl_add_u64 v[116:117], v[116:117], 0, s[82:83]
	s_mov_b32 m0, s2
	v_mov_b32_e32 v64, v113
	v_add_u32_e32 v115, 0, v115
	v_add_u32_e32 v114, 0, v114
	v_pk_mul_f32 v[34:35], v[34:35], v[2:3]
	v_pk_mul_f32 v[14:15], v[124:125], v[2:3]
	v_pk_mul_f32 v[18:19], v[134:135], v[10:11]
	v_pk_mul_f32 v[2:3], v[138:139], v[10:11]
	v_pk_mul_f32 v[6:7], v[144:145], v[10:11]
	v_pk_mul_f32 v[10:11], v[128:129], v[10:11]
	global_load_lds_dwordx4 v[116:117], off
	v_pk_mul_f32 v[0:1], v[136:137], v[8:9]
	v_add_u32_e32 v128, v115, v64
	v_add_u32_e32 v141, v114, v64
	v_pk_mul_f32 v[8:9], v[126:127], v[8:9]
	ds_read_b128 v[116:119], v128
	ds_read_b128 v[120:123], v128 offset:2048
	ds_read_b128 v[124:127], v128 offset:4096
	ds_read_b128 v[128:131], v128 offset:6144
	ds_read_b128 v[132:135], v141 offset:16384
	ds_read_b128 v[136:139], v141 offset:18432
	ds_read_b128 v[142:145], v141 offset:20480
	ds_read_b128 v[146:149], v141 offset:22528
	v_xor_b32_e32 v64, 64, v64
	s_waitcnt lgkmcnt(0)
;     ...
;         for (int ks = 0; ks < 2; ++ks) {
;           bf16x8 a[4], b[4];
;           const int fo = fb ^ (ks << 6);
; #pragma unroll
;           for (int i = 0; i < 4; ++i) a[i] = *(const bf16x8*)(sA + (wp * 64 + i * 16) * 128 + fo);
; #pragma unroll
;           for (int j = 0; j < 4; ++j) b[j] = *(const bf16x8*)(sB + (wq * 64 + j * 16) * 128 + fo);
; #pragma unroll
;           for (int i = 0; i < 4; ++i)
; #pragma unroll
;             for (int j = 0; j < 4; ++j) acc[i][j] = __builtin_amdgcn_mfma_f32_16x16x32_bf16(a[i], b[j], acc[i][j], 0, 0, 0);
	v_mfma_f32_16x16x32_bf16 v[16:19], v[128:131], v[132:135], v[16:19]
	v_mfma_f32_16x16x32_bf16 v[0:3], v[128:131], v[136:139], v[0:3]
	v_mfma_f32_16x16x32_bf16 v[4:7], v[128:131], v[142:145], v[4:7]
	v_mfma_f32_16x16x32_bf16 v[8:11], v[128:131], v[146:149], v[8:11]
	v_add_u32_e32 v128, v115, v64
	v_add_u32_e32 v64, v114, v64
	v_mfma_f32_16x16x32_bf16 v[60:63], v[116:119], v[132:135], v[60:63]
	v_mfma_f32_16x16x32_bf16 v[56:59], v[116:119], v[136:139], v[56:59]
	v_mfma_f32_16x16x32_bf16 v[52:55], v[116:119], v[142:145], v[52:55]
	v_mfma_f32_16x16x32_bf16 v[44:47], v[116:119], v[146:149], v[44:47]
	v_mfma_f32_16x16x32_bf16 v[48:51], v[120:123], v[132:135], v[48:51]
	v_mfma_f32_16x16x32_bf16 v[40:43], v[120:123], v[136:139], v[40:43]
	v_mfma_f32_16x16x32_bf16 v[36:39], v[120:123], v[142:145], v[36:39]
	v_mfma_f32_16x16x32_bf16 v[28:31], v[120:123], v[146:149], v[28:31]
	v_mfma_f32_16x16x32_bf16 v[32:35], v[124:127], v[132:135], v[32:35]
	v_mfma_f32_16x16x32_bf16 v[24:27], v[124:127], v[136:139], v[24:27]
	v_mfma_f32_16x16x32_bf16 v[20:23], v[124:127], v[142:145], v[20:23]
	v_mfma_f32_16x16x32_bf16 v[12:15], v[124:127], v[146:149], v[12:15]
	ds_read_b128 v[116:119], v128
	ds_read_b128 v[120:123], v128 offset:2048
	ds_read_b128 v[124:127], v128 offset:4096
	ds_read_b128 v[128:131], v128 offset:6144
	ds_read_b128 v[132:135], v64 offset:16384
	ds_read_b128 v[136:139], v64 offset:18432
	ds_read_b128 v[142:145], v64 offset:20480
	ds_read_b128 v[146:149], v64 offset:22528
	s_waitcnt vmcnt(0) lgkmcnt(0)
	s_barrier
	s_waitcnt lgkmcnt(0)
	v_mfma_f32_16x16x32_bf16 v[60:63], v[116:119], v[132:135], v[60:63]
	v_add_u32_e32 v64, v115, v113
	v_mfma_f32_16x16x32_bf16 v[56:59], v[116:119], v[136:139], v[56:59]
	v_mfma_f32_16x16x32_bf16 v[52:55], v[116:119], v[142:145], v[52:55]
	v_mfma_f32_16x16x32_bf16 v[44:47], v[116:119], v[146:149], v[44:47]
	v_mfma_f32_16x16x32_bf16 v[48:51], v[120:123], v[132:135], v[48:51]
	v_mfma_f32_16x16x32_bf16 v[40:43], v[120:123], v[136:139], v[40:43]
	v_mfma_f32_16x16x32_bf16 v[36:39], v[120:123], v[142:145], v[36:39]
	v_mfma_f32_16x16x32_bf16 v[28:31], v[120:123], v[146:149], v[28:31]
	v_mfma_f32_16x16x32_bf16 v[32:35], v[124:127], v[132:135], v[32:35]
	v_mfma_f32_16x16x32_bf16 v[24:27], v[124:127], v[136:139], v[24:27]
	v_mfma_f32_16x16x32_bf16 v[20:23], v[124:127], v[142:145], v[20:23]
	v_mfma_f32_16x16x32_bf16 v[12:15], v[124:127], v[146:149], v[12:15]
	v_mfma_f32_16x16x32_bf16 v[16:19], v[128:131], v[132:135], v[16:19]
	v_mfma_f32_16x16x32_bf16 v[0:3], v[128:131], v[136:139], v[0:3]
	v_mfma_f32_16x16x32_bf16 v[4:7], v[128:131], v[142:145], v[4:7]
	v_mfma_f32_16x16x32_bf16 v[8:11], v[128:131], v[146:149], v[8:11]
	ds_read_b128 v[116:119], v64 offset:32768
	ds_read_b128 v[120:123], v64 offset:34816
	ds_read_b128 v[124:127], v64 offset:36864
	ds_read_b128 v[128:131], v64 offset:38912
	v_add_u32_e32 v64, v114, v113
	ds_read_b128 v[132:135], v64 offset:49152
	ds_read_b128 v[136:139], v64 offset:51200
	ds_read_b128 v[142:145], v64 offset:53248
	ds_read_b128 v[146:149], v64 offset:55296
	v_xor_b32_e32 v64, 64, v113
	v_add_u32_e32 v113, v115, v64
	s_waitcnt lgkmcnt(0)
	v_mfma_f32_16x16x32_bf16 v[60:63], v[116:119], v[132:135], v[60:63]
	v_add_u32_e32 v64, v114, v64
	v_mfma_f32_16x16x32_bf16 v[56:59], v[116:119], v[136:139], v[56:59]
	v_mfma_f32_16x16x32_bf16 v[52:55], v[116:119], v[142:145], v[52:55]
	v_mfma_f32_16x16x32_bf16 v[44:47], v[116:119], v[146:149], v[44:47]
	v_mfma_f32_16x16x32_bf16 v[48:51], v[120:123], v[132:135], v[48:51]
	v_mfma_f32_16x16x32_bf16 v[40:43], v[120:123], v[136:139], v[40:43]
	v_mfma_f32_16x16x32_bf16 v[36:39], v[120:123], v[142:145], v[36:39]
	v_mfma_f32_16x16x32_bf16 v[28:31], v[120:123], v[146:149], v[28:31]
	v_mfma_f32_16x16x32_bf16 v[32:35], v[124:127], v[132:135], v[32:35]
	v_mfma_f32_16x16x32_bf16 v[24:27], v[124:127], v[136:139], v[24:27]
	v_mfma_f32_16x16x32_bf16 v[20:23], v[124:127], v[142:145], v[20:23]
	v_mfma_f32_16x16x32_bf16 v[12:15], v[124:127], v[146:149], v[12:15]
	v_mfma_f32_16x16x32_bf16 v[16:19], v[128:131], v[132:135], v[16:19]
	v_mfma_f32_16x16x32_bf16 v[0:3], v[128:131], v[136:139], v[0:3]
	v_mfma_f32_16x16x32_bf16 v[4:7], v[128:131], v[142:145], v[4:7]
	v_mfma_f32_16x16x32_bf16 v[8:11], v[128:131], v[146:149], v[8:11]
	ds_read_b128 v[116:119], v113 offset:32768
	ds_read_b128 v[120:123], v113 offset:34816
	ds_read_b128 v[124:127], v113 offset:36864
	ds_read_b128 v[128:131], v113 offset:38912
	v_mov_b32_e32 v113, v140
	ds_read_b128 v[132:135], v64 offset:49152
	ds_read_b128 v[136:139], v64 offset:51200
	ds_read_b128 v[142:145], v64 offset:53248
	ds_read_b128 v[146:149], v64 offset:55296
	s_waitcnt vmcnt(0) lgkmcnt(0)
	s_barrier
; __device__ __forceinline__ int opaque_tid() { int t = threadIdx.x; asm volatile("" : "+v"(t)); return t; }
; __device__ __forceinline__ void stage_acc(float* Cs, f32x4 (&acc)[4][4]) {
;   const int tid = opaque_tid(), lane = tid & 63, wave = tid >> 6, wp = wave >> 1, wq = wave & 1, lr = lane & 15, g = lane >> 4;
;   int sb = (wp * 64 + g * 4) * CS_LD + wq * 64 + lr;
;   asm volatile("" : "+v"(sb));
;   float* cb = Cs + sb;
; #pragma unroll
;   for (int i = 0; i < 4; ++i)
; #pragma unroll
;     for (int j = 0; j < 4; ++j)
; #pragma unroll
;       for (int r = 0; r < 4; ++r) cb[(i * 16 + r) * CS_LD + j * 16] = acc[i][j][r];
; __device__ __forceinline__ void phase_ret_passC(const Params& p, char* smem) {
;     ...
;       stage_acc(Cs, acc);
;       __syncthreads();
; #pragma unroll
;       for (int it = 0; it < 8; ++it) {
;         const int rw = it * 16 + rgrp;
;         const float4 v0 = *(const float4*)(Cs + rw * CS_LD + c16 * 8), v1 = *(const float4*)(Cs + rw * CS_LD + c16 * 8 + 4);
;         ssp[it] += (v0.x * v0.x + v0.y * v0.y) + (v0.z * v0.z + v0.w * v0.w) + (v1.x * v1.x + v1.y * v1.y) + (v1.z * v1.z + v1.w * v1.w);
;         u32x4 o;
;         o.x = pack2(v0.x, v0.y); o.y = pack2(v0.z, v0.w); o.z = pack2(v1.x, v1.y); o.w = pack2(v1.z, v1.w);
;         *(u32x4*)(M + (tok0 + rw) * 1024 + hh * 256 + eh * 128 + c16 * 8) = o;
;       }
	v_mfma_f32_16x16x32_bf16 v[60:63], v[116:119], v[132:135], v[60:63]
	v_lshrrev_b32_e32 v115, 2, v113
	v_lshrrev_b32_e32 v114, 1, v113
	v_and_b32_e32 v115, 12, v115
	v_and_b32_e32 v64, 64, v113
	v_and_or_b32 v114, v114, s89, v115
	v_mfma_f32_16x16x32_bf16 v[56:59], v[116:119], v[136:139], v[56:59]
	v_mad_u64_u32 v[114:115], s[84:85], v114, s92, v[64:65]
	v_and_or_b32 v64, v113, 15, v114
	v_mfma_f32_16x16x32_bf16 v[48:51], v[120:123], v[132:135], v[48:51]
	s_nop 0
	v_lshl_add_u32 v64, v64, 2, 0
	v_mfma_f32_16x16x32_bf16 v[40:43], v[120:123], v[136:139], v[40:43]
	s_nop 1
	ds_write2_b32 v64, v60, v56 offset1:16
	ds_write2_b32 v64, v61, v57 offset0:132 offset1:148
	v_add_u32_e32 v56, 0x400, v64
	v_mfma_f32_16x16x32_bf16 v[52:55], v[116:119], v[142:145], v[52:55]
	v_mfma_f32_16x16x32_bf16 v[44:47], v[116:119], v[146:149], v[44:47]
	ds_write2_b32 v56, v62, v58 offset0:8 offset1:24
	ds_write2_b32 v56, v63, v59 offset0:140 offset1:156
	s_nop 5
	ds_write2_b32 v64, v52, v44 offset0:32 offset1:48
	ds_write2_b32 v64, v53, v45 offset0:164 offset1:180
	ds_write2_b32 v56, v54, v46 offset0:40 offset1:56
	ds_write2_b32 v56, v55, v47 offset0:172 offset1:188
	v_add_u32_e32 v44, 0x2000, v64
	v_mfma_f32_16x16x32_bf16 v[32:35], v[124:127], v[132:135], v[32:35]
	ds_write2_b32 v44, v48, v40 offset0:64 offset1:80
	ds_write2_b32 v44, v49, v41 offset0:196 offset1:212
	v_add_u32_e32 v40, 0x2400, v64
	v_mfma_f32_16x16x32_bf16 v[24:27], v[124:127], v[136:139], v[24:27]
	v_mfma_f32_16x16x32_bf16 v[36:39], v[120:123], v[142:145], v[36:39]
	v_mfma_f32_16x16x32_bf16 v[28:31], v[120:123], v[146:149], v[28:31]
	ds_write2_b32 v40, v50, v42 offset0:72 offset1:88
	ds_write2_b32 v40, v51, v43 offset0:204 offset1:220
	s_nop 5
	ds_write2_b32 v44, v36, v28 offset0:96 offset1:112
	ds_write2_b32 v44, v37, v29 offset0:228 offset1:244
	ds_write2_b32 v40, v38, v30 offset0:104 offset1:120
	ds_write2_b32 v40, v39, v31 offset0:236 offset1:252
	v_add_u32_e32 v28, 0x4000, v64
	v_mfma_f32_16x16x32_bf16 v[20:23], v[124:127], v[142:145], v[20:23]
	ds_write2_b32 v28, v32, v24 offset0:128 offset1:144
	v_add_u32_e32 v24, 0x4400, v64
	ds_write2_b32 v24, v33, v25 offset0:4 offset1:20
	ds_write2_b32 v24, v34, v26 offset0:136 offset1:152
	v_mfma_f32_16x16x32_bf16 v[12:15], v[124:127], v[146:149], v[12:15]
	v_add_u32_e32 v25, 0x4800, v64
	ds_write2_b32 v25, v35, v27 offset0:12 offset1:28
	s_nop 5
	ds_write2_b32 v28, v20, v12 offset0:160 offset1:176
	ds_write2_b32 v24, v21, v13 offset0:36 offset1:52
	ds_write2_b32 v24, v22, v14 offset0:168 offset1:184
	ds_write2_b32 v25, v23, v15 offset0:44 offset1:60
	v_mfma_f32_16x16x32_bf16 v[16:19], v[128:131], v[132:135], v[16:19]
	v_add_u32_e32 v12, 0x6000, v64
	v_mfma_f32_16x16x32_bf16 v[0:3], v[128:131], v[136:139], v[0:3]
	v_mfma_f32_16x16x32_bf16 v[4:7], v[128:131], v[142:145], v[4:7]
	v_mfma_f32_16x16x32_bf16 v[8:11], v[128:131], v[146:149], v[8:11]
	s_nop 5
	ds_write2_b32 v12, v16, v0 offset0:192 offset1:208
	v_add_u32_e32 v0, 0x6400, v64
	ds_write2_b32 v0, v17, v1 offset0:68 offset1:84
	ds_write2_b32 v0, v18, v2 offset0:200 offset1:216
	v_add_u32_e32 v1, 0x6800, v64
	ds_write2_b32 v1, v19, v3 offset0:76 offset1:92
	ds_write2_b32 v12, v4, v8 offset0:224 offset1:240
	ds_write2_b32 v0, v5, v9 offset0:100 offset1:116
	ds_write2_b32 v0, v6, v10 offset0:232 offset1:248
	ds_write2_b32 v1, v7, v11 offset0:108 offset1:124
	s_waitcnt lgkmcnt(0)
	s_barrier
	ds_read_b128 v[2:5], v112
	ds_read_b128 v[6:9], v112 offset:16
	ds_read_b128 v[14:17], v112 offset:8448
	v_lshl_add_u64 v[0:1], s[14:15], 1, v[88:89]
	v_lshl_add_u64 v[18:19], v[0:1], 0, v[90:91]
	s_waitcnt lgkmcnt(2)
	v_cvt_pk_bf16_f32 v10, v2, v3
	v_cvt_pk_bf16_f32 v11, v4, v5
	v_mov_b32_e32 v13, v2
	s_waitcnt lgkmcnt(0)
	v_mov_b32_e32 v2, v15
	v_mov_b32_e32 v23, v4
	v_mov_b32_e32 v4, v17
	v_pk_mul_f32 v[20:21], v[2:3], v[2:3]
	v_pk_mul_f32 v[24:25], v[4:5], v[4:5]
	ds_read_b128 v[2:5], v112 offset:8464
	v_mov_b32_e32 v12, v14
	v_mov_b32_e32 v22, v16
	v_pk_fma_f32 v[12:13], v[12:13], v[12:13], v[20:21]
	v_pk_fma_f32 v[20:21], v[22:23], v[22:23], v[24:25]
	s_waitcnt lgkmcnt(0)
	v_mov_b32_e32 v22, v3
	v_mov_b32_e32 v23, v7
	v_pk_add_f32 v[12:13], v[12:13], v[20:21]
	v_mov_b32_e32 v20, v2
	v_mov_b32_e32 v21, v6
	v_pk_mul_f32 v[22:23], v[22:23], v[22:23]
	s_movk_i32 s14, 0x80
	v_pk_fma_f32 v[20:21], v[20:21], v[20:21], v[22:23]
	v_mov_b32_e32 v22, v5
	v_mov_b32_e32 v23, v9
	v_pk_add_f32 v[12:13], v[12:13], v[20:21]
	v_mov_b32_e32 v20, v4
	v_mov_b32_e32 v21, v8
	v_pk_mul_f32 v[22:23], v[22:23], v[22:23]
	s_nop 0
	v_pk_fma_f32 v[20:21], v[20:21], v[20:21], v[22:23]
	s_nop 0
	v_pk_add_f32 v[20:21], v[12:13], v[20:21]
	v_cvt_pk_bf16_f32 v12, v6, v7
	v_cvt_pk_bf16_f32 v13, v8, v9
	v_cvt_pk_bf16_f32 v6, v14, v15
	v_cvt_pk_bf16_f32 v7, v16, v17
	v_cvt_pk_bf16_f32 v8, v2, v3
	v_cvt_pk_bf16_f32 v9, v4, v5
	v_lshl_add_u64 v[2:3], v[0:1], 0, v[92:93]
	global_store_dwordx4 v[18:19], v[10:13], off
	global_store_dwordx4 v[2:3], v[6:9], off
	ds_read_b128 v[2:5], v112 offset:16896
	ds_read_b128 v[10:13], v112 offset:25344
	v_pk_add_f32 v[106:107], v[106:107], v[20:21]
	v_lshl_add_u64 v[18:19], v[0:1], 0, v[94:95]
	s_waitcnt lgkmcnt(1)
	v_cvt_pk_bf16_f32 v6, v2, v3
	v_cvt_pk_bf16_f32 v7, v4, v5
	v_mov_b32_e32 v9, v2
	s_waitcnt lgkmcnt(0)
	v_mov_b32_e32 v2, v11
	v_mov_b32_e32 v23, v4
	v_mov_b32_e32 v4, v13
	v_pk_mul_f32 v[20:21], v[2:3], v[2:3]
	v_pk_mul_f32 v[24:25], v[4:5], v[4:5]
	ds_read_b128 v[2:5], v112 offset:16912
	ds_read_b128 v[14:17], v112 offset:25360
	v_mov_b32_e32 v8, v10
	v_mov_b32_e32 v22, v12
	v_pk_fma_f32 v[8:9], v[8:9], v[8:9], v[20:21]
	v_pk_fma_f32 v[20:21], v[22:23], v[22:23], v[24:25]
	s_waitcnt lgkmcnt(0)
; __device__ __forceinline__ void phase_ret_passC(const Params& p, char* smem) {
;     ...
; #pragma unroll
;       for (int it = 0; it < 8; ++it) {
;         const int rw = it * 16 + rgrp;
;         const float4 v0 = *(const float4*)(Cs + rw * CS_LD + c16 * 8), v1 = *(const float4*)(Cs + rw * CS_LD + c16 * 8 + 4);
;         ssp[it] += (v0.x * v0.x + v0.y * v0.y) + (v0.z * v0.z + v0.w * v0.w) + (v1.x * v1.x + v1.y * v1.y) + (v1.z * v1.z + v1.w * v1.w);
;         u32x4 o;
;         o.x = pack2(v0.x, v0.y); o.y = pack2(v0.z, v0.w); o.z = pack2(v1.x, v1.y); o.w = pack2(v1.z, v1.w);
;         *(u32x4*)(M + (tok0 + rw) * 1024 + hh * 256 + eh * 128 + c16 * 8) = o;
;       }
;       __syncthreads();
	v_mov_b32_e32 v22, v15
	v_mov_b32_e32 v23, v3
	v_pk_add_f32 v[8:9], v[8:9], v[20:21]
	v_mov_b32_e32 v20, v14
	v_mov_b32_e32 v21, v2
	v_pk_mul_f32 v[22:23], v[22:23], v[22:23]
	s_nop 0
	v_pk_fma_f32 v[20:21], v[20:21], v[20:21], v[22:23]
	v_mov_b32_e32 v22, v17
	v_mov_b32_e32 v23, v5
	v_pk_add_f32 v[8:9], v[8:9], v[20:21]
	v_mov_b32_e32 v20, v16
	v_mov_b32_e32 v21, v4
	v_pk_mul_f32 v[22:23], v[22:23], v[22:23]
	s_nop 0
	v_pk_fma_f32 v[20:21], v[20:21], v[20:21], v[22:23]
	s_nop 0
	v_pk_add_f32 v[20:21], v[8:9], v[20:21]
	v_cvt_pk_bf16_f32 v8, v2, v3
	v_cvt_pk_bf16_f32 v9, v4, v5
	global_store_dwordx4 v[18:19], v[6:9], off
	v_cvt_pk_bf16_f32 v2, v10, v11
	v_cvt_pk_bf16_f32 v3, v12, v13
	v_cvt_pk_bf16_f32 v4, v14, v15
	v_cvt_pk_bf16_f32 v5, v16, v17
	v_lshl_add_u64 v[6:7], v[0:1], 0, v[96:97]
	global_store_dwordx4 v[6:7], v[2:5], off
	ds_read_b128 v[2:5], v112 offset:33792
	ds_read_b128 v[10:13], v112 offset:42240
	v_pk_add_f32 v[86:87], v[86:87], v[20:21]
	v_lshl_add_u64 v[18:19], v[0:1], 0, v[98:99]
	s_waitcnt lgkmcnt(1)
	v_cvt_pk_bf16_f32 v6, v2, v3
	v_cvt_pk_bf16_f32 v7, v4, v5
	v_mov_b32_e32 v9, v2
	s_waitcnt lgkmcnt(0)
	v_mov_b32_e32 v2, v11
	v_mov_b32_e32 v23, v4
	v_mov_b32_e32 v4, v13
	v_pk_mul_f32 v[20:21], v[2:3], v[2:3]
	v_pk_mul_f32 v[24:25], v[4:5], v[4:5]
	ds_read_b128 v[2:5], v112 offset:33808
	ds_read_b128 v[14:17], v112 offset:42256
	v_mov_b32_e32 v8, v10
	v_mov_b32_e32 v22, v12
	v_pk_fma_f32 v[8:9], v[8:9], v[8:9], v[20:21]
	v_pk_fma_f32 v[20:21], v[22:23], v[22:23], v[24:25]
	s_waitcnt lgkmcnt(0)
	v_mov_b32_e32 v22, v15
	v_mov_b32_e32 v23, v3
	v_pk_add_f32 v[8:9], v[8:9], v[20:21]
	v_mov_b32_e32 v20, v14
	v_mov_b32_e32 v21, v2
	v_pk_mul_f32 v[22:23], v[22:23], v[22:23]
	s_nop 0
	v_pk_fma_f32 v[20:21], v[20:21], v[20:21], v[22:23]
	v_mov_b32_e32 v22, v17
	v_mov_b32_e32 v23, v5
	v_pk_add_f32 v[8:9], v[8:9], v[20:21]
	v_mov_b32_e32 v20, v16
	v_mov_b32_e32 v21, v4
	v_pk_mul_f32 v[22:23], v[22:23], v[22:23]
	s_nop 0
	v_pk_fma_f32 v[20:21], v[20:21], v[20:21], v[22:23]
	s_nop 0
	v_pk_add_f32 v[20:21], v[8:9], v[20:21]
	v_cvt_pk_bf16_f32 v8, v2, v3
	v_cvt_pk_bf16_f32 v9, v4, v5
	global_store_dwordx4 v[18:19], v[6:9], off
	v_cvt_pk_bf16_f32 v2, v10, v11
	v_cvt_pk_bf16_f32 v3, v12, v13
	v_cvt_pk_bf16_f32 v4, v14, v15
	v_cvt_pk_bf16_f32 v5, v16, v17
	v_lshl_add_u64 v[6:7], v[0:1], 0, v[100:101]
	global_store_dwordx4 v[6:7], v[2:5], off
	ds_read_b128 v[2:5], v112 offset:50688
	ds_read_b128 v[6:9], v112 offset:50704
	ds_read_b128 v[14:17], v112 offset:59136
	v_pk_add_f32 v[84:85], v[84:85], v[20:21]
	v_lshl_add_u64 v[18:19], v[0:1], 0, v[102:103]
	s_waitcnt lgkmcnt(2)
	v_cvt_pk_bf16_f32 v10, v2, v3
	v_cvt_pk_bf16_f32 v11, v4, v5
	v_mov_b32_e32 v13, v2
	s_waitcnt lgkmcnt(0)
	v_mov_b32_e32 v2, v15
	v_mov_b32_e32 v23, v4
	v_mov_b32_e32 v4, v17
	v_pk_mul_f32 v[20:21], v[2:3], v[2:3]
	v_pk_mul_f32 v[24:25], v[4:5], v[4:5]
	ds_read_b128 v[2:5], v112 offset:59152
	v_mov_b32_e32 v12, v14
	v_mov_b32_e32 v22, v16
	v_pk_fma_f32 v[12:13], v[12:13], v[12:13], v[20:21]
	v_pk_fma_f32 v[20:21], v[22:23], v[22:23], v[24:25]
	s_waitcnt lgkmcnt(0)
	v_mov_b32_e32 v22, v3
	v_mov_b32_e32 v23, v7
	v_pk_add_f32 v[12:13], v[12:13], v[20:21]
	v_mov_b32_e32 v20, v2
	v_mov_b32_e32 v21, v6
	v_pk_mul_f32 v[22:23], v[22:23], v[22:23]
	v_lshl_add_u64 v[0:1], v[0:1], 0, v[104:105]
	v_pk_fma_f32 v[20:21], v[20:21], v[20:21], v[22:23]
	v_mov_b32_e32 v22, v5
	v_mov_b32_e32 v23, v9
	v_pk_add_f32 v[12:13], v[12:13], v[20:21]
	v_mov_b32_e32 v20, v4
	v_mov_b32_e32 v21, v8
	v_pk_mul_f32 v[22:23], v[22:23], v[22:23]
	s_nop 0
	v_pk_fma_f32 v[20:21], v[20:21], v[20:21], v[22:23]
	s_nop 0
	v_pk_add_f32 v[20:21], v[12:13], v[20:21]
	v_cvt_pk_bf16_f32 v12, v6, v7
	v_cvt_pk_bf16_f32 v13, v8, v9
	v_pk_add_f32 v[66:67], v[66:67], v[20:21]
	v_cvt_pk_bf16_f32 v6, v14, v15
	v_cvt_pk_bf16_f32 v7, v16, v17
	v_cvt_pk_bf16_f32 v8, v2, v3
	v_cvt_pk_bf16_f32 v9, v4, v5
	global_store_dwordx4 v[18:19], v[10:13], off
	global_store_dwordx4 v[0:1], v[6:9], off
	s_barrier
	s_cbranch_vccnz .LBB0_1690
; __device__ __forceinline__ void phase_ret_passC(const Params& p, char* smem) {
;     ...
; #pragma unroll
;     for (int it = 0; it < 8; ++it) ssp[it] = rsqrtf(row16_sum(ssp[it]) * (1.f / 256.f) + 1e-6f);
; #pragma unroll 1
;     for (int eh = 0; eh < 2; ++eh) {
;       const int col = hh * 256 + eh * 128 + c16 * 8;
;       const float4 g0 = *(const float4*)(gng + col), g1 = *(const float4*)(gng + col + 4);
; #pragma unroll
;       for (int it = 0; it < 8; ++it) {
;         const int rw = it * 16 + rgrp;
;         const float rstd = ssp[it];
;         ushort_t* mp = M + (tok0 + rw) * 1024 + col;
;         const u32x4 mv = *(const u32x4*)mp, gv = *(const u32x4*)(G + (tok0 + rw) * 1024 + col);
	v_mov_b32_dpp v1, v107 quad_perm:[1,0,3,2] row_mask:0xf bank_mask:0xf bound_ctrl:1
	v_mov_b32_dpp v0, v106 quad_perm:[1,0,3,2] row_mask:0xf bank_mask:0xf bound_ctrl:1
	v_pk_add_f32 v[0:1], v[106:107], v[0:1]
	v_lshlrev_b64 v[10:11], 10, v[78:79]
	v_lshlrev_b64 v[40:41], 10, v[80:81]
	v_mov_b32_dpp v3, v1 quad_perm:[2,3,0,1] row_mask:0xf bank_mask:0xf bound_ctrl:1
	v_mov_b32_dpp v2, v0 quad_perm:[2,3,0,1] row_mask:0xf bank_mask:0xf bound_ctrl:1
	v_pk_add_f32 v[0:1], v[0:1], v[2:3]
	v_lshlrev_b64 v[42:43], 10, v[82:83]
	v_lshlrev_b64 v[38:39], 1, v[10:11]
	v_mov_b32_dpp v3, v1 row_half_mirror row_mask:0xf bank_mask:0xf bound_ctrl:1
	v_mov_b32_dpp v2, v0 row_half_mirror row_mask:0xf bank_mask:0xf bound_ctrl:1
	v_pk_add_f32 v[0:1], v[0:1], v[2:3]
	v_lshlrev_b64 v[40:41], 1, v[40:41]
	v_lshlrev_b64 v[42:43], 1, v[42:43]
	v_mov_b32_dpp v3, v1 row_mirror row_mask:0xf bank_mask:0xf bound_ctrl:1
	v_mov_b32_dpp v2, v0 row_mirror row_mask:0xf bank_mask:0xf bound_ctrl:1
	v_pk_add_f32 v[0:1], v[0:1], v[2:3]
	v_mov_b64_e32 v[2:3], s[88:89]
	v_pk_fma_f32 v[0:1], v[0:1], s[86:87], v[2:3] op_sel_hi:[1,0,0]
	s_nop 0
	v_mul_f32_e32 v4, 0x4b800000, v1
	v_cmp_gt_f32_e32 vcc, s87, v1
	v_cmp_gt_f32_e64 s[6:7], s87, v0
	s_nop 0
	v_cndmask_b32_e32 v1, v1, v4, vcc
	v_rsq_f32_e32 v1, v1
	v_mul_f32_e32 v4, 0x4b800000, v0
	v_cndmask_b32_e64 v0, v0, v4, s[6:7]
	v_rsq_f32_e32 v6, v0
	v_mul_f32_e32 v0, 0x45800000, v1
	v_cndmask_b32_e32 v12, v1, v0, vcc
	v_mov_b32_dpp v1, v87 quad_perm:[1,0,3,2] row_mask:0xf bank_mask:0xf bound_ctrl:1
	v_mov_b32_dpp v0, v86 quad_perm:[1,0,3,2] row_mask:0xf bank_mask:0xf bound_ctrl:1
	v_pk_add_f32 v[0:1], v[86:87], v[0:1]
	v_mul_f32_e32 v7, 0x45800000, v6
	v_cndmask_b32_e64 v14, v6, v7, s[6:7]
	v_mov_b32_dpp v5, v1 quad_perm:[2,3,0,1] row_mask:0xf bank_mask:0xf bound_ctrl:1
	v_mov_b32_dpp v4, v0 quad_perm:[2,3,0,1] row_mask:0xf bank_mask:0xf bound_ctrl:1
	v_pk_add_f32 v[0:1], v[0:1], v[4:5]
	v_mov_b32_e32 v13, v12
	v_mov_b32_e32 v15, v14
	v_mov_b32_dpp v5, v1 row_half_mirror row_mask:0xf bank_mask:0xf bound_ctrl:1
	v_mov_b32_dpp v4, v0 row_half_mirror row_mask:0xf bank_mask:0xf bound_ctrl:1
	v_pk_add_f32 v[0:1], v[0:1], v[4:5]
	s_nop 1
	v_mov_b32_dpp v5, v1 row_mirror row_mask:0xf bank_mask:0xf bound_ctrl:1
	v_mov_b32_dpp v4, v0 row_mirror row_mask:0xf bank_mask:0xf bound_ctrl:1
	v_pk_add_f32 v[0:1], v[0:1], v[4:5]
	s_nop 0
	v_pk_fma_f32 v[0:1], v[0:1], s[86:87], v[2:3] op_sel_hi:[1,0,0]
	s_nop 0
	v_mul_f32_e32 v4, 0x4b800000, v1
	v_cmp_gt_f32_e32 vcc, s87, v1
	v_cmp_gt_f32_e64 s[8:9], s87, v0
	s_nop 0
	v_cndmask_b32_e32 v1, v1, v4, vcc
	v_rsq_f32_e32 v1, v1
	v_mul_f32_e32 v4, 0x4b800000, v0
	v_cndmask_b32_e64 v0, v0, v4, s[8:9]
	v_rsq_f32_e32 v8, v0
	v_mul_f32_e32 v0, 0x45800000, v1
	v_cndmask_b32_e32 v16, v1, v0, vcc
	v_mov_b32_dpp v1, v85 quad_perm:[1,0,3,2] row_mask:0xf bank_mask:0xf bound_ctrl:1
	v_mov_b32_dpp v0, v84 quad_perm:[1,0,3,2] row_mask:0xf bank_mask:0xf bound_ctrl:1
	v_pk_add_f32 v[0:1], v[84:85], v[0:1]
	v_mul_f32_e32 v6, 0x45800000, v8
	v_cndmask_b32_e64 v18, v8, v6, s[8:9]
	v_mov_b32_dpp v5, v1 quad_perm:[2,3,0,1] row_mask:0xf bank_mask:0xf bound_ctrl:1
	v_mov_b32_dpp v4, v0 quad_perm:[2,3,0,1] row_mask:0xf bank_mask:0xf bound_ctrl:1
	v_pk_add_f32 v[0:1], v[0:1], v[4:5]
	v_lshlrev_b64 v[8:9], 10, v[76:77]
	v_mov_b32_e32 v17, v16
	v_mov_b32_dpp v5, v1 row_half_mirror row_mask:0xf bank_mask:0xf bound_ctrl:1
	v_mov_b32_dpp v4, v0 row_half_mirror row_mask:0xf bank_mask:0xf bound_ctrl:1
	v_pk_add_f32 v[0:1], v[0:1], v[4:5]
	v_mov_b32_e32 v19, v18
	v_lshlrev_b64 v[36:37], 1, v[8:9]
	v_mov_b32_dpp v5, v1 row_mirror row_mask:0xf bank_mask:0xf bound_ctrl:1
	v_mov_b32_dpp v4, v0 row_mirror row_mask:0xf bank_mask:0xf bound_ctrl:1
	v_pk_add_f32 v[0:1], v[0:1], v[4:5]
	s_nop 0
	v_pk_fma_f32 v[0:1], v[0:1], s[86:87], v[2:3] op_sel_hi:[1,0,0]
	s_nop 0
	v_mul_f32_e32 v4, 0x4b800000, v1
	v_cmp_gt_f32_e32 vcc, s87, v1
	v_cmp_gt_f32_e64 s[6:7], s87, v0
	s_nop 0
	v_cndmask_b32_e32 v1, v1, v4, vcc
	v_rsq_f32_e32 v1, v1
	v_mul_f32_e32 v4, 0x4b800000, v0
	v_cndmask_b32_e64 v0, v0, v4, s[6:7]
	v_rsq_f32_e32 v7, v0
	v_mul_f32_e32 v0, 0x45800000, v1
	v_cndmask_b32_e32 v20, v1, v0, vcc
	v_mov_b32_dpp v1, v67 quad_perm:[1,0,3,2] row_mask:0xf bank_mask:0xf bound_ctrl:1
	v_mov_b32_dpp v0, v66 quad_perm:[1,0,3,2] row_mask:0xf bank_mask:0xf bound_ctrl:1
	v_pk_add_f32 v[0:1], v[66:67], v[0:1]
	v_mul_f32_e32 v6, 0x45800000, v7
	v_cndmask_b32_e64 v22, v7, v6, s[6:7]
	v_mov_b32_dpp v5, v1 quad_perm:[2,3,0,1] row_mask:0xf bank_mask:0xf bound_ctrl:1
	v_mov_b32_dpp v4, v0 quad_perm:[2,3,0,1] row_mask:0xf bank_mask:0xf bound_ctrl:1
	v_pk_add_f32 v[0:1], v[0:1], v[4:5]
	v_lshlrev_b64 v[6:7], 10, v[74:75]
	v_mov_b32_e32 v21, v20
	v_mov_b32_dpp v5, v1 row_half_mirror row_mask:0xf bank_mask:0xf bound_ctrl:1
	v_mov_b32_dpp v4, v0 row_half_mirror row_mask:0xf bank_mask:0xf bound_ctrl:1
	v_pk_add_f32 v[0:1], v[0:1], v[4:5]
	v_mov_b32_e32 v23, v22
	v_or_b32_e32 v74, s0, v110
	v_mov_b32_dpp v5, v1 row_mirror row_mask:0xf bank_mask:0xf bound_ctrl:1
	v_mov_b32_dpp v4, v0 row_mirror row_mask:0xf bank_mask:0xf bound_ctrl:1
	v_pk_add_f32 v[0:1], v[0:1], v[4:5]
	v_lshlrev_b64 v[4:5], 10, v[72:73]
	v_pk_fma_f32 v[0:1], v[0:1], s[86:87], v[2:3] op_sel_hi:[1,0,0]
	s_mov_b32 s0, 0
	v_mul_f32_e32 v2, 0x4b800000, v1
	v_cmp_gt_f32_e32 vcc, s87, v1
	v_cmp_gt_f32_e64 s[8:9], s87, v0
	s_mov_b64 s[6:7], -1
	v_cndmask_b32_e32 v1, v1, v2, vcc
	v_mul_f32_e32 v2, 0x4b800000, v0
	v_rsq_f32_e32 v1, v1
	v_cndmask_b32_e64 v0, v0, v2, s[8:9]
	v_rsq_f32_e32 v0, v0
	v_lshlrev_b64 v[32:33], 1, v[4:5]
	v_mul_f32_e32 v2, 0x45800000, v1
	v_cndmask_b32_e32 v24, v1, v2, vcc
	v_mul_f32_e32 v1, 0x45800000, v0
	v_cndmask_b32_e64 v26, v0, v1, s[8:9]
	v_lshlrev_b64 v[0:1], 10, v[68:69]
	v_lshlrev_b64 v[2:3], 10, v[70:71]
	v_mov_b32_e32 v25, v24
	v_mov_b32_e32 v27, v26
	v_lshlrev_b64 v[28:29], 1, v[0:1]
	v_lshlrev_b64 v[30:31], 1, v[2:3]
	v_lshlrev_b64 v[34:35], 1, v[6:7]
